# v16
# baseline (speedup 1.0000x reference)
; #define LAS __attribute__((address_space(3)))
; __device__ __forceinline__ unsigned cvt_pk_bf16(float lo, float hi) { unsigned r; asm volatile("v_cvt_pk_bf16_f32 %0, %1, %2" : "=v"(r) : "v"(lo), "v"(hi)); return r; }
; __device__ __forceinline__ float gelu_t(float x) { const float u = 1.5957691216f * (x + 0.044715f * x * x * x); return x * sigm(u); }
; __device__ __forceinline__ float dpp_shr1(float old, float src) { return __int_as_float(__builtin_amdgcn_update_dpp(__float_as_int(old), __float_as_int(src), 0x111, 0xf, 0xf, false)); }
;     __device__ __forceinline__ void operator()(AccT& acc, const Unit& u, int wr, int wc, int fr, int fq) const {
;     ...
;         for (int n = 0; n < 2; ++n) {
;             const int cg = u.pn * 128 + lcol + 4 * n;
;             f32x4 wgt[2][3], bia[2];
; #pragma unroll
;             for (int bj = 0; bj < 2; ++bj) { const int ch = cg + bj * FF; bia[bj] = *(const f32x4*)(cb + ch);
; #pragma unroll
;                 for (int k = 0; k < 3; ++k) wgt[bj][k] = *(const f32x4*)(cw + (size_t)k * FF2 + ch); }
; #pragma unroll
;             for (int ai = 0; ai < 2; ++ai) {
;                 f32x4 hv[2]; hv[0] = (f32x4){0.f, 0.f, 0.f, 0.f}; hv[1] = hv[0];
;                 const bool has_pred = (wr == 1) || (ai == 1);
;                 const int pa = (wr == 1) ? ai : 0, pw = (wr == 1) ? 0 : 1;
;                 if (has_pred && fr >= 14) { hv[0] = *(const LAS f32x4*)(xl + xidx(pa, pw, wc, fr - 14, fq, 0, n)); hv[1] = *(const LAS f32x4*)(xl + xidx(pa, pw, wc, fr - 14, fq, 1, n)); }
; #pragma unroll
;                 for (int m = 0; m < 4; ++m) {
;                     f32x4 c2[2];
; #pragma unroll
;                     for (int bj = 0; bj < 2; ++bj) { const f32x4 cur = acc[ai][bj][m][n]; const f32x4 pv = (m == 0) ? hv[bj] : acc[ai][bj][m == 0 ? 0 : m - 1][n];
; #pragma unroll
;                         for (int j = 0; j < 4; ++j) { const float p1 = dpp_shr1(dpp_ror1(pv[j]), cur[j]), p2 = dpp_shr2(dpp_ror2(pv[j]), cur[j]);
;                             c2[bj][j] = bia[bj][j] + wgt[bj][0][j] * p2 + wgt[bj][1][j] * p1 + wgt[bj][2][j] * cur[j]; } }
;                     u32x2 w; w.x = cvt_pk_bf16(gelu_t(c2[0][0]) * c2[1][0], gelu_t(c2[0][1]) * c2[1][1]); w.y = cvt_pk_bf16(gelu_t(c2[0][2]) * c2[1][2], gelu_t(c2[0][3]) * c2[1][3]);
.LBB0_786:
	s_or_b64 exec, exec, s[12:13]
	v_lshl_or_b32 v186, s3, 7, v109
	v_ashrrev_i32_e32 v187, 31, v186
	v_lshlrev_b64 v[122:123], 2, v[186:187]
	v_lshl_add_u64 v[188:189], s[28:29], 0, v[122:123]
	v_lshl_add_u64 v[190:191], s[30:31], 0, v[122:123]
	v_add_co_u32_e32 v122, vcc, 0x15000, v188
	s_waitcnt lgkmcnt(0)
	s_barrier
	s_nop 0
	v_addc_co_u32_e32 v123, vcc, 0, v189, vcc
	global_load_dwordx4 v[200:203], v[190:191], off offset:16
	global_load_dwordx4 v[118:121], v[190:191], off
	global_load_dwordx4 v[204:207], v[188:189], off offset:16
	global_load_dwordx4 v[142:145], v[188:189], off
	global_load_dwordx4 v[208:211], v[122:123], off offset:2064
	global_load_dwordx4 v[146:149], v[122:123], off offset:2048
	v_add_co_u32_e32 v122, vcc, 0x2b000, v188
	v_add_u32_e32 v163, 0x3fffffc8, v108
	s_nop 0
	v_addc_co_u32_e32 v123, vcc, 0, v189, vcc
	global_load_dwordx4 v[212:215], v[122:123], off offset:16
	global_load_dwordx4 v[150:153], v[122:123], off
	v_add_co_u32_e32 v122, vcc, 0xa000, v190
	s_and_b64 s[12:13], s[26:27], s[6:7]
	s_nop 0
	v_addc_co_u32_e32 v123, vcc, 0, v191, vcc
	v_add_co_u32_e32 v130, vcc, 0xa000, v188
	global_load_dwordx4 v[216:219], v[122:123], off offset:3088
	global_load_dwordx4 v[122:125], v[122:123], off offset:3072
	s_nop 0
	v_addc_co_u32_e32 v131, vcc, 0, v189, vcc
	v_add_co_u32_e32 v132, vcc, 0x20000, v188
	v_mov_b32_e32 v162, 0
	s_nop 0
	v_addc_co_u32_e32 v133, vcc, 0, v189, vcc
	v_add_co_u32_e32 v134, vcc, 0x35000, v188
	global_load_dwordx4 v[220:223], v[130:131], off offset:3088
	global_load_dwordx4 v[138:141], v[130:131], off offset:3072
	s_nop 0
	global_load_dwordx4 v[224:227], v[132:133], off offset:1040
	global_load_dwordx4 v[130:133], v[132:133], off offset:1024
	v_addc_co_u32_e32 v135, vcc, 0, v189, vcc
	global_load_dwordx4 v[228:231], v[134:135], off offset:3088
	global_load_dwordx4 v[134:137], v[134:135], off offset:3072
	v_lshl_add_u32 v184, v163, 6, s90
	v_mov_b32_e32 v164, 0
	v_mov_b32_e32 v165, 0
	v_mov_b32_e32 v166, 0
	v_mov_b32_e32 v167, 0
	v_mov_b32_e32 v168, 0
	v_mov_b32_e32 v169, 0
	v_mov_b32_e32 v170, 0
	v_mov_b32_e32 v171, 0
	s_and_saveexec_b64 s[16:17], s[12:13]
	s_cbranch_execz .LBB0_788
	ds_read_b128 v[168:171], v184
	ds_read_b128 v[164:167], v184 offset:32
.LBB0_788:
	s_or_b64 exec, exec, s[16:17]
	s_waitcnt lgkmcnt(0)
	v_mov_b32_dpp v109, v168 row_ror:2 row_mask:0xf bank_mask:0xf
	v_mov_b32_dpp v108, v168 row_ror:1 row_mask:0xf bank_mask:0xf
	v_mov_b32_dpp v109, v158 row_shr:2 row_mask:0xf bank_mask:0xf
	v_mov_b32_dpp v108, v158 row_shr:1 row_mask:0xf bank_mask:0xf
	s_waitcnt vmcnt(0)
	v_fma_f32 v109, v142, v109, v118
	v_fmac_f32_e32 v109, v146, v108
	v_mov_b32_dpp v168, v169 row_ror:2 row_mask:0xf bank_mask:0xf
	v_fmac_f32_e32 v109, v158, v150
	v_mov_b32_dpp v108, v169 row_ror:1 row_mask:0xf bank_mask:0xf
	v_mov_b32_dpp v168, v159 row_shr:2 row_mask:0xf bank_mask:0xf
	v_fma_f32 v168, v143, v168, v119
	v_mov_b32_dpp v108, v159 row_shr:1 row_mask:0xf bank_mask:0xf
	v_fmac_f32_e32 v168, v147, v108
	v_mov_b32_dpp v169, v170 row_ror:2 row_mask:0xf bank_mask:0xf
	v_fmac_f32_e32 v168, v159, v151
	v_mov_b32_dpp v108, v170 row_ror:1 row_mask:0xf bank_mask:0xf
	v_mov_b32_dpp v169, v160 row_shr:2 row_mask:0xf bank_mask:0xf
	v_fma_f32 v169, v144, v169, v120
	v_mov_b32_dpp v108, v160 row_shr:1 row_mask:0xf bank_mask:0xf
	v_fmac_f32_e32 v169, v148, v108
	v_mov_b32_dpp v170, v171 row_ror:2 row_mask:0xf bank_mask:0xf
	v_mul_f32_e32 v172, 0x3d372713, v168
	v_mov_b32_dpp v108, v171 row_ror:1 row_mask:0xf bank_mask:0xf
	v_mov_b32_dpp v170, v161 row_shr:2 row_mask:0xf bank_mask:0xf
	v_mov_b32_dpp v108, v161 row_shr:1 row_mask:0xf bank_mask:0xf
	v_fma_f32 v170, v145, v170, v121
	v_mov_b32_dpp v171, v164 row_ror:2 row_mask:0xf bank_mask:0xf
	v_fmac_f32_e32 v170, v149, v108
	v_mov_b32_dpp v171, v104 row_shr:2 row_mask:0xf bank_mask:0xf
	v_mul_f32_e32 v172, v168, v172
	v_mov_b32_dpp v108, v164 row_ror:1 row_mask:0xf bank_mask:0xf
	v_fma_f32 v164, v138, v171, v122
	v_mov_b32_dpp v108, v104 row_shr:1 row_mask:0xf bank_mask:0xf
	v_fmac_f32_e32 v164, v130, v108
	v_mov_b32_dpp v171, v165 row_ror:2 row_mask:0xf bank_mask:0xf
	v_fma_f32 v172, v168, v172, v168
	v_mov_b32_dpp v171, v105 row_shr:2 row_mask:0xf bank_mask:0xf
	v_mov_b32_dpp v108, v165 row_ror:1 row_mask:0xf bank_mask:0xf
	v_fma_f32 v165, v139, v171, v123
	v_mov_b32_dpp v108, v105 row_shr:1 row_mask:0xf bank_mask:0xf
	v_fmac_f32_e32 v165, v131, v108
	v_mov_b32_dpp v171, v166 row_ror:2 row_mask:0xf bank_mask:0xf
	v_mul_f32_e32 v172, 0x3fcc422a, v172
	v_mov_b32_dpp v171, v106 row_shr:2 row_mask:0xf bank_mask:0xf
	v_mov_b32_dpp v108, v166 row_ror:1 row_mask:0xf bank_mask:0xf
	v_fma_f32 v166, v140, v171, v124
	v_mov_b32_dpp v108, v106 row_shr:1 row_mask:0xf bank_mask:0xf
	v_fmac_f32_e32 v166, v132, v108
	v_mov_b32_dpp v171, v167 row_ror:2 row_mask:0xf bank_mask:0xf
	v_mul_f32_e32 v172, 0xbfb8aa3b, v172
	v_mov_b32_dpp v171, v107 row_shr:2 row_mask:0xf bank_mask:0xf
	v_mov_b32_dpp v108, v167 row_ror:1 row_mask:0xf bank_mask:0xf
	v_fma_f32 v167, v141, v171, v125
	v_mul_f32_e32 v171, 0x3d372713, v109
	v_mul_f32_e32 v171, v109, v171
	v_fma_f32 v171, v109, v171, v109
	v_mul_f32_e32 v171, 0x3fcc422a, v171
	v_mul_f32_e32 v171, 0xbfb8aa3b, v171
	v_exp_f32_e32 v171, v171
	v_exp_f32_e32 v172, v172
	v_mov_b32_dpp v108, v107 row_shr:1 row_mask:0xf bank_mask:0xf
	v_fmac_f32_e32 v167, v133, v108
	v_add_f32_e32 v108, 1.0, v171
	v_rcp_f32_e32 v108, v108
	v_add_f32_e32 v171, 1.0, v172
	v_rcp_f32_e32 v171, v171
	v_fmac_f32_e32 v169, v160, v152
	v_fmac_f32_e32 v170, v161, v153
	v_fmac_f32_e32 v164, v104, v134
	v_mul_f32_e32 v108, v109, v108
	v_mul_f32_e32 v108, v108, v164
; __device__ __forceinline__ unsigned cvt_pk_bf16(float lo, float hi) { unsigned r; asm volatile("v_cvt_pk_bf16_f32 %0, %1, %2" : "=v"(r) : "v"(lo), "v"(hi)); return r; }
; __device__ __forceinline__ float gelu_t(float x) { const float u = 1.5957691216f * (x + 0.044715f * x * x * x); return x * sigm(u); }
; __device__ __forceinline__ float dpp_shr1(float old, float src) { return __int_as_float(__builtin_amdgcn_update_dpp(__float_as_int(old), __float_as_int(src), 0x111, 0xf, 0xf, false)); }
; __device__ __forceinline__ float dpp_shr2(float old, float src) { return __int_as_float(__builtin_amdgcn_update_dpp(__float_as_int(old), __float_as_int(src), 0x112, 0xf, 0xf, false)); }
; __device__ __forceinline__ float dpp_ror1(float src) { return __int_as_float(__builtin_amdgcn_update_dpp(0, __float_as_int(src), 0x121, 0xf, 0xf, false)); }
; __device__ __forceinline__ float dpp_ror2(float src) { return __int_as_float(__builtin_amdgcn_update_dpp(0, __float_as_int(src), 0x122, 0xf, 0xf, false)); }
;     __device__ __forceinline__ void operator()(AccT& acc, const Unit& u, int wr, int wc, int fr, int fq) const {
;     ...
;                 for (int m = 0; m < 4; ++m) {
;                     f32x4 c2[2];
; #pragma unroll
;                     for (int bj = 0; bj < 2; ++bj) { const f32x4 cur = acc[ai][bj][m][n]; const f32x4 pv = (m == 0) ? hv[bj] : acc[ai][bj][m == 0 ? 0 : m - 1][n];
; #pragma unroll
;                         for (int j = 0; j < 4; ++j) { const float p1 = dpp_shr1(dpp_ror1(pv[j]), cur[j]), p2 = dpp_shr2(dpp_ror2(pv[j]), cur[j]);
;                             c2[bj][j] = bia[bj][j] + wgt[bj][0][j] * p2 + wgt[bj][1][j] * p1 + wgt[bj][2][j] * cur[j]; } }
;                     u32x2 w; w.x = cvt_pk_bf16(gelu_t(c2[0][0]) * c2[1][0], gelu_t(c2[0][1]) * c2[1][1]); w.y = cvt_pk_bf16(gelu_t(c2[0][2]) * c2[1][2], gelu_t(c2[0][3]) * c2[1][3]);
	v_mul_f32_e32 v109, v168, v171
	v_mul_f32_e32 v164, 0x3d372713, v169
	v_mul_f32_e32 v168, 0x3d372713, v170
	v_mul_f32_e32 v164, v169, v164
	v_mul_f32_e32 v168, v170, v168
	v_fma_f32 v164, v169, v164, v169
	v_fma_f32 v168, v170, v168, v170
	v_mul_f32_e32 v164, 0x3fcc422a, v164
	v_mul_f32_e32 v168, 0x3fcc422a, v168
	v_mul_f32_e32 v164, 0xbfb8aa3b, v164
	v_mul_f32_e32 v168, 0xbfb8aa3b, v168
	v_exp_f32_e32 v164, v164
	v_exp_f32_e32 v168, v168
	v_fmac_f32_e32 v165, v105, v135
	v_mul_f32_e32 v109, v109, v165
	v_add_f32_e32 v164, 1.0, v164
	v_add_f32_e32 v165, 1.0, v168
	v_rcp_f32_e32 v164, v164
	v_rcp_f32_e32 v165, v165
	v_fmac_f32_e32 v166, v106, v136
	v_fmac_f32_e32 v167, v107, v137
	v_cvt_pk_bf16_f32 v108, v108, v109
	v_mul_f32_e32 v109, v169, v164
	v_mul_f32_e32 v164, v170, v165
	v_mul_f32_e32 v109, v109, v166
	v_mul_f32_e32 v164, v164, v167
	v_cvt_pk_bf16_f32 v109, v109, v164
	s_nop 0
	v_mov_b32_dpp v165, v158 row_ror:2 row_mask:0xf bank_mask:0xf
	v_mov_b32_dpp v164, v158 row_ror:1 row_mask:0xf bank_mask:0xf
	s_nop 0
	v_mov_b32_dpp v165, v154 row_shr:2 row_mask:0xf bank_mask:0xf
	v_mov_b32_dpp v164, v154 row_shr:1 row_mask:0xf bank_mask:0xf
	v_fma_f32 v158, v142, v165, v118
	v_fmac_f32_e32 v158, v146, v164
	v_mov_b32_dpp v165, v159 row_ror:2 row_mask:0xf bank_mask:0xf
	v_fmac_f32_e32 v158, v154, v150
	v_mov_b32_dpp v164, v159 row_ror:1 row_mask:0xf bank_mask:0xf
	v_mov_b32_dpp v165, v155 row_shr:2 row_mask:0xf bank_mask:0xf
	v_fma_f32 v159, v143, v165, v119
	v_mov_b32_dpp v164, v155 row_shr:1 row_mask:0xf bank_mask:0xf
	v_fmac_f32_e32 v159, v147, v164
	v_mov_b32_dpp v165, v160 row_ror:2 row_mask:0xf bank_mask:0xf
	v_fmac_f32_e32 v159, v155, v151
	v_mov_b32_dpp v164, v160 row_ror:1 row_mask:0xf bank_mask:0xf
	v_mov_b32_dpp v165, v156 row_shr:2 row_mask:0xf bank_mask:0xf
	v_fma_f32 v160, v144, v165, v120
	v_mov_b32_dpp v164, v156 row_shr:1 row_mask:0xf bank_mask:0xf
	v_fmac_f32_e32 v160, v148, v164
	v_mov_b32_dpp v165, v161 row_ror:2 row_mask:0xf bank_mask:0xf
	v_mul_f32_e32 v166, 0x3d372713, v159
	v_mov_b32_dpp v164, v161 row_ror:1 row_mask:0xf bank_mask:0xf
	v_mov_b32_dpp v165, v157 row_shr:2 row_mask:0xf bank_mask:0xf
	v_fma_f32 v161, v145, v165, v121
	v_mov_b32_dpp v164, v157 row_shr:1 row_mask:0xf bank_mask:0xf
	v_fmac_f32_e32 v161, v149, v164
	v_mov_b32_dpp v165, v104 row_ror:2 row_mask:0xf bank_mask:0xf
	v_mul_f32_e32 v166, v159, v166
	v_mov_b32_dpp v164, v104 row_ror:1 row_mask:0xf bank_mask:0xf
	v_mov_b32_dpp v165, v126 row_shr:2 row_mask:0xf bank_mask:0xf
	v_fma_f32 v104, v138, v165, v122
	v_mov_b32_dpp v164, v126 row_shr:1 row_mask:0xf bank_mask:0xf
	v_fmac_f32_e32 v104, v130, v164
	v_mov_b32_dpp v165, v105 row_ror:2 row_mask:0xf bank_mask:0xf
	v_fma_f32 v166, v159, v166, v159
	v_mov_b32_dpp v164, v105 row_ror:1 row_mask:0xf bank_mask:0xf
	v_mov_b32_dpp v165, v127 row_shr:2 row_mask:0xf bank_mask:0xf
	v_fma_f32 v105, v139, v165, v123
	v_mov_b32_dpp v164, v127 row_shr:1 row_mask:0xf bank_mask:0xf
	v_fmac_f32_e32 v105, v131, v164
	v_mov_b32_dpp v165, v106 row_ror:2 row_mask:0xf bank_mask:0xf
	v_mul_f32_e32 v166, 0x3fcc422a, v166
	v_mov_b32_dpp v164, v106 row_ror:1 row_mask:0xf bank_mask:0xf
	v_mov_b32_dpp v165, v128 row_shr:2 row_mask:0xf bank_mask:0xf
	v_fma_f32 v165, v140, v165, v124
	v_mov_b32_dpp v164, v128 row_shr:1 row_mask:0xf bank_mask:0xf
	v_fmac_f32_e32 v165, v132, v164
	v_mul_f32_e32 v166, 0xbfb8aa3b, v166
	v_mov_b32_dpp v164, v107 row_ror:2 row_mask:0xf bank_mask:0xf
	v_mov_b32_dpp v106, v107 row_ror:1 row_mask:0xf bank_mask:0xf
	v_exp_f32_e32 v166, v166
	v_mov_b32_dpp v164, v129 row_shr:2 row_mask:0xf bank_mask:0xf
	v_fma_f32 v107, v141, v164, v125
	v_mul_f32_e32 v164, 0x3d372713, v158
	v_mul_f32_e32 v164, v158, v164
	v_fma_f32 v164, v158, v164, v158
	v_mul_f32_e32 v164, 0x3fcc422a, v164
	v_mul_f32_e32 v164, 0xbfb8aa3b, v164
	v_exp_f32_e32 v164, v164
	v_mov_b32_dpp v106, v129 row_shr:1 row_mask:0xf bank_mask:0xf
	v_fmac_f32_e32 v107, v133, v106
	v_fmac_f32_e32 v160, v156, v152
	v_add_f32_e32 v106, 1.0, v164
	v_rcp_f32_e32 v106, v106
	v_add_f32_e32 v164, 1.0, v166
	v_rcp_f32_e32 v164, v164
	v_fmac_f32_e32 v161, v157, v153
	v_fmac_f32_e32 v104, v126, v134
	v_mul_f32_e32 v106, v158, v106
	v_mul_f32_e32 v158, 0x3d372713, v160
	v_mul_f32_e32 v104, v106, v104
	v_mul_f32_e32 v106, v159, v164
	v_mul_f32_e32 v158, v160, v158
	v_mul_f32_e32 v159, 0x3d372713, v161
	v_fma_f32 v158, v160, v158, v160
	v_mul_f32_e32 v159, v161, v159
	v_mul_f32_e32 v158, 0x3fcc422a, v158
	v_fma_f32 v159, v161, v159, v161
	v_mul_f32_e32 v158, 0xbfb8aa3b, v158
	v_mul_f32_e32 v159, 0x3fcc422a, v159
	v_exp_f32_e32 v158, v158
	v_mul_f32_e32 v159, 0xbfb8aa3b, v159
	v_exp_f32_e32 v159, v159
	v_fmac_f32_e32 v105, v127, v135
	v_mul_f32_e32 v105, v106, v105
	v_add_f32_e32 v106, 1.0, v158
	v_rcp_f32_e32 v158, v106
	v_add_f32_e32 v106, 1.0, v159
	v_rcp_f32_e32 v159, v106
	v_fmac_f32_e32 v107, v129, v137
	v_cvt_pk_bf16_f32 v106, v104, v105
	v_fmac_f32_e32 v165, v128, v136
	v_mul_f32_e32 v105, v161, v159
	v_mul_f32_e32 v104, v160, v158
	v_mul_f32_e32 v105, v105, v107
	v_mul_f32_e32 v104, v104, v165
	v_cvt_pk_bf16_f32 v107, v104, v105
	v_mov_b32_e32 v164, 0
	v_mov_b32_dpp v105, v154 row_ror:2 row_mask:0xf bank_mask:0xf
	v_mov_b32_dpp v104, v154 row_ror:1 row_mask:0xf bank_mask:0xf
	v_mov_b32_dpp v105, v114 row_shr:2 row_mask:0xf bank_mask:0xf
	v_mov_b32_dpp v104, v114 row_shr:1 row_mask:0xf bank_mask:0xf
	v_fma_f32 v105, v142, v105, v118
	v_fmac_f32_e32 v105, v146, v104
	v_mov_b32_dpp v154, v155 row_ror:2 row_mask:0xf bank_mask:0xf
	v_fmac_f32_e32 v105, v114, v150
	v_mov_b32_dpp v104, v155 row_ror:1 row_mask:0xf bank_mask:0xf
	v_mov_b32_dpp v154, v115 row_shr:2 row_mask:0xf bank_mask:0xf
; __device__ __forceinline__ unsigned cvt_pk_bf16(float lo, float hi) { unsigned r; asm volatile("v_cvt_pk_bf16_f32 %0, %1, %2" : "=v"(r) : "v"(lo), "v"(hi)); return r; }
; __device__ __forceinline__ float gelu_t(float x) { const float u = 1.5957691216f * (x + 0.044715f * x * x * x); return x * sigm(u); }
; __device__ __forceinline__ float dpp_shr1(float old, float src) { return __int_as_float(__builtin_amdgcn_update_dpp(__float_as_int(old), __float_as_int(src), 0x111, 0xf, 0xf, false)); }
; __device__ __forceinline__ float dpp_shr2(float old, float src) { return __int_as_float(__builtin_amdgcn_update_dpp(__float_as_int(old), __float_as_int(src), 0x112, 0xf, 0xf, false)); }
; __device__ __forceinline__ float dpp_ror1(float src) { return __int_as_float(__builtin_amdgcn_update_dpp(0, __float_as_int(src), 0x121, 0xf, 0xf, false)); }
; __device__ __forceinline__ float dpp_ror2(float src) { return __int_as_float(__builtin_amdgcn_update_dpp(0, __float_as_int(src), 0x122, 0xf, 0xf, false)); }
;     __device__ __forceinline__ void operator()(AccT& acc, const Unit& u, int wr, int wc, int fr, int fq) const {
;     ...
;                 for (int m = 0; m < 4; ++m) {
;                     f32x4 c2[2];
; #pragma unroll
;                     for (int bj = 0; bj < 2; ++bj) { const f32x4 cur = acc[ai][bj][m][n]; const f32x4 pv = (m == 0) ? hv[bj] : acc[ai][bj][m == 0 ? 0 : m - 1][n];
; #pragma unroll
;                         for (int j = 0; j < 4; ++j) { const float p1 = dpp_shr1(dpp_ror1(pv[j]), cur[j]), p2 = dpp_shr2(dpp_ror2(pv[j]), cur[j]);
;                             c2[bj][j] = bia[bj][j] + wgt[bj][0][j] * p2 + wgt[bj][1][j] * p1 + wgt[bj][2][j] * cur[j]; } }
;                     u32x2 w; w.x = cvt_pk_bf16(gelu_t(c2[0][0]) * c2[1][0], gelu_t(c2[0][1]) * c2[1][1]); w.y = cvt_pk_bf16(gelu_t(c2[0][2]) * c2[1][2], gelu_t(c2[0][3]) * c2[1][3]);
	v_fma_f32 v154, v143, v154, v119
	v_mov_b32_dpp v104, v115 row_shr:1 row_mask:0xf bank_mask:0xf
	v_fmac_f32_e32 v154, v147, v104
	v_mov_b32_dpp v155, v156 row_ror:2 row_mask:0xf bank_mask:0xf
	v_fmac_f32_e32 v154, v115, v151
	v_mov_b32_dpp v104, v156 row_ror:1 row_mask:0xf bank_mask:0xf
	v_mov_b32_dpp v155, v116 row_shr:2 row_mask:0xf bank_mask:0xf
	v_fma_f32 v155, v144, v155, v120
	v_mov_b32_dpp v104, v116 row_shr:1 row_mask:0xf bank_mask:0xf
	v_fmac_f32_e32 v155, v148, v104
	v_mov_b32_dpp v156, v157 row_ror:2 row_mask:0xf bank_mask:0xf
	v_mul_f32_e32 v158, 0x3d372713, v154
	v_mov_b32_dpp v104, v157 row_ror:1 row_mask:0xf bank_mask:0xf
	v_mov_b32_dpp v156, v117 row_shr:2 row_mask:0xf bank_mask:0xf
	v_mov_b32_dpp v104, v117 row_shr:1 row_mask:0xf bank_mask:0xf
	v_fma_f32 v156, v145, v156, v121
	v_mov_b32_dpp v157, v126 row_ror:2 row_mask:0xf bank_mask:0xf
	v_fmac_f32_e32 v156, v149, v104
	v_mov_b32_dpp v157, v100 row_shr:2 row_mask:0xf bank_mask:0xf
	v_mul_f32_e32 v158, v154, v158
	v_mov_b32_dpp v104, v126 row_ror:1 row_mask:0xf bank_mask:0xf
	v_fma_f32 v126, v138, v157, v122
	v_mov_b32_dpp v104, v100 row_shr:1 row_mask:0xf bank_mask:0xf
	v_fmac_f32_e32 v126, v130, v104
	v_mov_b32_dpp v157, v127 row_ror:2 row_mask:0xf bank_mask:0xf
	v_fma_f32 v158, v154, v158, v154
	v_mov_b32_dpp v157, v101 row_shr:2 row_mask:0xf bank_mask:0xf
	v_mov_b32_dpp v104, v127 row_ror:1 row_mask:0xf bank_mask:0xf
	v_fma_f32 v127, v139, v157, v123
	v_mov_b32_dpp v104, v101 row_shr:1 row_mask:0xf bank_mask:0xf
	v_fmac_f32_e32 v127, v131, v104
	v_mov_b32_dpp v157, v128 row_ror:2 row_mask:0xf bank_mask:0xf
	v_mul_f32_e32 v158, 0x3fcc422a, v158
	v_mov_b32_dpp v157, v102 row_shr:2 row_mask:0xf bank_mask:0xf
	v_mov_b32_dpp v104, v128 row_ror:1 row_mask:0xf bank_mask:0xf
	v_fma_f32 v128, v140, v157, v124
	v_mov_b32_dpp v104, v102 row_shr:1 row_mask:0xf bank_mask:0xf
	v_fmac_f32_e32 v128, v132, v104
	v_mov_b32_dpp v157, v129 row_ror:2 row_mask:0xf bank_mask:0xf
	v_mul_f32_e32 v158, 0xbfb8aa3b, v158
	v_mov_b32_dpp v157, v103 row_shr:2 row_mask:0xf bank_mask:0xf
	v_mov_b32_dpp v104, v129 row_ror:1 row_mask:0xf bank_mask:0xf
	v_fma_f32 v129, v141, v157, v125
	v_mul_f32_e32 v157, 0x3d372713, v105
	v_mul_f32_e32 v157, v105, v157
	v_fma_f32 v157, v105, v157, v105
	v_mul_f32_e32 v157, 0x3fcc422a, v157
	v_mul_f32_e32 v157, 0xbfb8aa3b, v157
	v_exp_f32_e32 v157, v157
	v_exp_f32_e32 v158, v158
	v_mov_b32_dpp v104, v103 row_shr:1 row_mask:0xf bank_mask:0xf
	v_fmac_f32_e32 v129, v133, v104
	v_add_f32_e32 v104, 1.0, v157
	v_rcp_f32_e32 v104, v104
	v_add_f32_e32 v157, 1.0, v158
	v_rcp_f32_e32 v157, v157
	v_fmac_f32_e32 v155, v116, v152
	v_fmac_f32_e32 v156, v117, v153
	v_fmac_f32_e32 v126, v100, v134
	v_mul_f32_e32 v104, v105, v104
	v_mul_f32_e32 v104, v104, v126
	v_mul_f32_e32 v105, v154, v157
	v_mul_f32_e32 v126, 0x3d372713, v155
	v_mul_f32_e32 v154, 0x3d372713, v156
	v_mul_f32_e32 v126, v155, v126
	v_mul_f32_e32 v154, v156, v154
	v_fma_f32 v126, v155, v126, v155
	v_fma_f32 v154, v156, v154, v156
	v_mul_f32_e32 v126, 0x3fcc422a, v126
	v_mul_f32_e32 v154, 0x3fcc422a, v154
	v_mul_f32_e32 v126, 0xbfb8aa3b, v126
	v_mul_f32_e32 v154, 0xbfb8aa3b, v154
	v_exp_f32_e32 v126, v126
	v_exp_f32_e32 v154, v154
	v_fmac_f32_e32 v127, v101, v135
	v_mul_f32_e32 v105, v105, v127
	v_add_f32_e32 v126, 1.0, v126
	v_add_f32_e32 v127, 1.0, v154
	v_rcp_f32_e32 v126, v126
	v_rcp_f32_e32 v127, v127
	v_fmac_f32_e32 v128, v102, v136
	v_fmac_f32_e32 v129, v103, v137
	v_cvt_pk_bf16_f32 v104, v104, v105
	v_mul_f32_e32 v105, v155, v126
	v_mul_f32_e32 v126, v156, v127
	v_mul_f32_e32 v105, v105, v128
	v_mul_f32_e32 v126, v126, v129
	v_cvt_pk_bf16_f32 v105, v105, v126
	v_lshl_add_u32 v154, v163, 6, s91
	v_mov_b32_dpp v127, v114 row_ror:2 row_mask:0xf bank_mask:0xf
	v_mov_b32_dpp v126, v114 row_ror:1 row_mask:0xf bank_mask:0xf
	v_mov_b32_e32 v163, 0
	v_mov_b32_dpp v127, v110 row_shr:2 row_mask:0xf bank_mask:0xf
	v_mov_b32_dpp v126, v110 row_shr:1 row_mask:0xf bank_mask:0xf
	v_fma_f32 v114, v142, v127, v118
	v_fmac_f32_e32 v114, v146, v126
	v_fmac_f32_e32 v114, v110, v150
	v_mov_b32_dpp v126, v115 row_ror:2 row_mask:0xf bank_mask:0xf
	v_mov_b32_e32 v165, 0
	v_mov_b32_dpp v110, v115 row_ror:1 row_mask:0xf bank_mask:0xf
	v_mov_b32_dpp v126, v111 row_shr:2 row_mask:0xf bank_mask:0xf
	v_fma_f32 v115, v143, v126, v119
	v_mov_b32_dpp v110, v111 row_shr:1 row_mask:0xf bank_mask:0xf
	v_fmac_f32_e32 v115, v147, v110
	v_fmac_f32_e32 v115, v111, v151
	s_nop 0
	v_mov_b32_dpp v111, v116 row_ror:2 row_mask:0xf bank_mask:0xf
	v_mov_b32_dpp v110, v116 row_ror:1 row_mask:0xf bank_mask:0xf
	s_nop 0
	v_mov_b32_dpp v111, v112 row_shr:2 row_mask:0xf bank_mask:0xf
	v_mov_b32_dpp v110, v112 row_shr:1 row_mask:0xf bank_mask:0xf
	v_fma_f32 v111, v144, v111, v120
	v_fmac_f32_e32 v111, v148, v110
	v_fmac_f32_e32 v111, v112, v152
	s_nop 0
	v_mov_b32_dpp v112, v117 row_ror:2 row_mask:0xf bank_mask:0xf
	v_mov_b32_dpp v110, v117 row_ror:1 row_mask:0xf bank_mask:0xf
	s_nop 0
	v_mov_b32_dpp v112, v113 row_shr:2 row_mask:0xf bank_mask:0xf
	v_mov_b32_dpp v110, v113 row_shr:1 row_mask:0xf bank_mask:0xf
	v_fma_f32 v112, v145, v112, v121
	v_fmac_f32_e32 v112, v149, v110
	v_fmac_f32_e32 v112, v113, v153
	s_nop 0
	v_mov_b32_dpp v113, v100 row_ror:2 row_mask:0xf bank_mask:0xf
	v_mov_b32_dpp v110, v100 row_ror:1 row_mask:0xf bank_mask:0xf
	s_nop 0
	v_mov_b32_dpp v113, v96 row_shr:2 row_mask:0xf bank_mask:0xf
	v_mov_b32_dpp v110, v96 row_shr:1 row_mask:0xf bank_mask:0xf
	v_fma_f32 v100, v138, v113, v122
	v_fmac_f32_e32 v100, v130, v110
	v_fmac_f32_e32 v100, v96, v134
	v_mov_b32_dpp v110, v101 row_ror:2 row_mask:0xf bank_mask:0xf
	s_nop 0
; #define LAS __attribute__((address_space(3)))
; __device__ __forceinline__ unsigned cvt_pk_bf16(float lo, float hi) { unsigned r; asm volatile("v_cvt_pk_bf16_f32 %0, %1, %2" : "=v"(r) : "v"(lo), "v"(hi)); return r; }
; __device__ __forceinline__ float gelu_t(float x) { const float u = 1.5957691216f * (x + 0.044715f * x * x * x); return x * sigm(u); }
; __device__ __forceinline__ float dpp_shr1(float old, float src) { return __int_as_float(__builtin_amdgcn_update_dpp(__float_as_int(old), __float_as_int(src), 0x111, 0xf, 0xf, false)); }
; __device__ __forceinline__ float dpp_shr2(float old, float src) { return __int_as_float(__builtin_amdgcn_update_dpp(__float_as_int(old), __float_as_int(src), 0x112, 0xf, 0xf, false)); }
; __device__ __forceinline__ float dpp_ror1(float src) { return __int_as_float(__builtin_amdgcn_update_dpp(0, __float_as_int(src), 0x121, 0xf, 0xf, false)); }
; __device__ __forceinline__ float dpp_ror2(float src) { return __int_as_float(__builtin_amdgcn_update_dpp(0, __float_as_int(src), 0x122, 0xf, 0xf, false)); }
;     __device__ __forceinline__ void operator()(AccT& acc, const Unit& u, int wr, int wc, int fr, int fq) const {
;     ...
;             for (int ai = 0; ai < 2; ++ai) {
;                 f32x4 hv[2]; hv[0] = (f32x4){0.f, 0.f, 0.f, 0.f}; hv[1] = hv[0];
;                 const bool has_pred = (wr == 1) || (ai == 1);
;                 const int pa = (wr == 1) ? ai : 0, pw = (wr == 1) ? 0 : 1;
;                 if (has_pred && fr >= 14) { hv[0] = *(const LAS f32x4*)(xl + xidx(pa, pw, wc, fr - 14, fq, 0, n)); hv[1] = *(const LAS f32x4*)(xl + xidx(pa, pw, wc, fr - 14, fq, 1, n)); }
; #pragma unroll
;                 for (int m = 0; m < 4; ++m) {
;                     f32x4 c2[2];
; #pragma unroll
;                     for (int bj = 0; bj < 2; ++bj) { const f32x4 cur = acc[ai][bj][m][n]; const f32x4 pv = (m == 0) ? hv[bj] : acc[ai][bj][m == 0 ? 0 : m - 1][n];
; #pragma unroll
;                         for (int j = 0; j < 4; ++j) { const float p1 = dpp_shr1(dpp_ror1(pv[j]), cur[j]), p2 = dpp_shr2(dpp_ror2(pv[j]), cur[j]);
;                             c2[bj][j] = bia[bj][j] + wgt[bj][0][j] * p2 + wgt[bj][1][j] * p1 + wgt[bj][2][j] * cur[j]; } }
;                     u32x2 w; w.x = cvt_pk_bf16(gelu_t(c2[0][0]) * c2[1][0], gelu_t(c2[0][1]) * c2[1][1]); w.y = cvt_pk_bf16(gelu_t(c2[0][2]) * c2[1][2], gelu_t(c2[0][3]) * c2[1][3]);
	v_mov_b32_dpp v96, v101 row_ror:1 row_mask:0xf bank_mask:0xf
	v_mov_b32_dpp v110, v97 row_shr:2 row_mask:0xf bank_mask:0xf
	v_fma_f32 v101, v139, v110, v123
	v_mov_b32_dpp v96, v97 row_shr:1 row_mask:0xf bank_mask:0xf
	v_fmac_f32_e32 v101, v131, v96
	v_fmac_f32_e32 v101, v97, v135
	s_nop 0
	v_mov_b32_dpp v97, v102 row_ror:2 row_mask:0xf bank_mask:0xf
	v_mov_b32_dpp v96, v102 row_ror:1 row_mask:0xf bank_mask:0xf
	s_nop 0
	v_mov_b32_dpp v97, v98 row_shr:2 row_mask:0xf bank_mask:0xf
	v_mov_b32_dpp v96, v98 row_shr:1 row_mask:0xf bank_mask:0xf
	v_fma_f32 v97, v140, v97, v124
	v_fmac_f32_e32 v97, v132, v96
	v_fmac_f32_e32 v97, v98, v136
	s_nop 0
	v_mov_b32_dpp v98, v103 row_ror:2 row_mask:0xf bank_mask:0xf
	v_mov_b32_dpp v96, v103 row_ror:1 row_mask:0xf bank_mask:0xf
	v_mul_f32_e32 v103, 0x3d372713, v115
	v_mov_b32_dpp v98, v99 row_shr:2 row_mask:0xf bank_mask:0xf
	v_fma_f32 v102, v141, v98, v125
	v_mul_f32_e32 v98, 0x3d372713, v114
	v_mul_f32_e32 v98, v114, v98
	v_fma_f32 v98, v114, v98, v114
	v_mul_f32_e32 v98, 0x3fcc422a, v98
	v_mul_f32_e32 v98, 0xbfb8aa3b, v98
	v_exp_f32_e32 v98, v98
	v_mov_b32_dpp v96, v99 row_shr:1 row_mask:0xf bank_mask:0xf
	v_fmac_f32_e32 v102, v133, v96
	v_mul_f32_e32 v103, v115, v103
	v_add_f32_e32 v96, 1.0, v98
	v_rcp_f32_e32 v96, v96
	v_fma_f32 v103, v115, v103, v115
	v_fmac_f32_e32 v102, v99, v137
	v_mul_f32_e32 v99, 0x3d372713, v111
	v_mul_f32_e32 v96, v114, v96
	v_mul_f32_e32 v103, 0x3fcc422a, v103
	v_mul_f32_e32 v96, v96, v100
	v_mul_f32_e32 v99, v111, v99
	v_mul_f32_e32 v100, 0x3d372713, v112
	v_mul_f32_e32 v103, 0xbfb8aa3b, v103
	v_fma_f32 v99, v111, v99, v111
	v_mul_f32_e32 v100, v112, v100
	v_exp_f32_e32 v103, v103
	v_mul_f32_e32 v99, 0x3fcc422a, v99
	v_fma_f32 v100, v112, v100, v112
	v_mul_f32_e32 v99, 0xbfb8aa3b, v99
	v_mul_f32_e32 v100, 0x3fcc422a, v100
	v_exp_f32_e32 v99, v99
	v_mul_f32_e32 v100, 0xbfb8aa3b, v100
	v_exp_f32_e32 v100, v100
	v_add_f32_e32 v98, 1.0, v103
	v_rcp_f32_e32 v98, v98
	v_add_f32_e32 v99, 1.0, v99
	v_rcp_f32_e32 v99, v99
	v_add_f32_e32 v100, 1.0, v100
	v_rcp_f32_e32 v100, v100
	v_mul_f32_e32 v98, v115, v98
	v_mul_f32_e32 v98, v98, v101
	v_cvt_pk_bf16_f32 v98, v96, v98
	v_mul_f32_e32 v96, v111, v99
	v_mul_f32_e32 v96, v96, v97
	v_mul_f32_e32 v97, v112, v100
	v_mul_f32_e32 v97, v97, v102
	v_mov_b32_e32 v100, 0
	v_mov_b32_e32 v101, 0
	v_mov_b32_e32 v102, 0
	v_mov_b32_e32 v103, 0
	v_cvt_pk_bf16_f32 v99, v96, v97
	s_and_saveexec_b64 s[16:17], s[6:7]
	s_cbranch_execz .LBB0_790
	ds_read_b128 v[100:103], v154
	ds_read_b128 v[162:165], v154 offset:32
.LBB0_790:
	s_or_b64 exec, exec, s[16:17]
	s_waitcnt lgkmcnt(1)
	v_mov_b32_dpp v97, v100 row_ror:2 row_mask:0xf bank_mask:0xf
	v_mov_b32_dpp v96, v100 row_ror:1 row_mask:0xf bank_mask:0xf
	v_mov_b32_dpp v97, v92 row_shr:2 row_mask:0xf bank_mask:0xf
	v_mov_b32_dpp v96, v92 row_shr:1 row_mask:0xf bank_mask:0xf
	v_fma_f32 v97, v142, v97, v118
	v_fmac_f32_e32 v97, v146, v96
	v_mov_b32_dpp v100, v101 row_ror:2 row_mask:0xf bank_mask:0xf
	v_fmac_f32_e32 v97, v92, v150
	v_mov_b32_dpp v96, v101 row_ror:1 row_mask:0xf bank_mask:0xf
	v_mov_b32_dpp v100, v93 row_shr:2 row_mask:0xf bank_mask:0xf
	v_fma_f32 v100, v143, v100, v119
	v_mov_b32_dpp v96, v93 row_shr:1 row_mask:0xf bank_mask:0xf
	v_fmac_f32_e32 v100, v147, v96
	v_mov_b32_dpp v101, v102 row_ror:2 row_mask:0xf bank_mask:0xf
	v_fmac_f32_e32 v100, v93, v151
	v_mov_b32_dpp v96, v102 row_ror:1 row_mask:0xf bank_mask:0xf
	v_mov_b32_dpp v101, v94 row_shr:2 row_mask:0xf bank_mask:0xf
	v_fma_f32 v101, v144, v101, v120
	v_mov_b32_dpp v96, v94 row_shr:1 row_mask:0xf bank_mask:0xf
	v_fmac_f32_e32 v101, v148, v96
	v_mov_b32_dpp v102, v103 row_ror:2 row_mask:0xf bank_mask:0xf
	s_waitcnt lgkmcnt(0)
	v_mov_b32_dpp v110, v163 row_ror:2 row_mask:0xf bank_mask:0xf
	v_mov_b32_dpp v96, v103 row_ror:1 row_mask:0xf bank_mask:0xf
	v_mov_b32_dpp v102, v95 row_shr:2 row_mask:0xf bank_mask:0xf
	v_fma_f32 v102, v145, v102, v121
	v_mov_b32_dpp v96, v95 row_shr:1 row_mask:0xf bank_mask:0xf
	v_fmac_f32_e32 v102, v149, v96
	v_mov_b32_dpp v103, v162 row_ror:2 row_mask:0xf bank_mask:0xf
	v_mul_f32_e32 v113, 0x3d372713, v97
	v_mov_b32_dpp v96, v162 row_ror:1 row_mask:0xf bank_mask:0xf
	v_mov_b32_dpp v103, v88 row_shr:2 row_mask:0xf bank_mask:0xf
	v_fma_f32 v103, v138, v103, v122
	v_mov_b32_dpp v96, v88 row_shr:1 row_mask:0xf bank_mask:0xf
	v_fmac_f32_e32 v103, v130, v96
	v_mov_b32_dpp v110, v89 row_shr:2 row_mask:0xf bank_mask:0xf
	v_mul_f32_e32 v113, v97, v113
	v_mov_b32_dpp v96, v163 row_ror:1 row_mask:0xf bank_mask:0xf
	v_mul_f32_e32 v114, 0x3d372713, v100
	v_fma_f32 v110, v139, v110, v123
	v_mov_b32_dpp v96, v89 row_shr:1 row_mask:0xf bank_mask:0xf
	v_fma_f32 v113, v97, v113, v97
	v_mul_f32_e32 v114, v100, v114
	v_fmac_f32_e32 v110, v131, v96
	v_mov_b32_dpp v111, v164 row_ror:2 row_mask:0xf bank_mask:0xf
	v_mul_f32_e32 v113, 0x3fcc422a, v113
	v_fma_f32 v114, v100, v114, v100
	v_mov_b32_dpp v96, v164 row_ror:1 row_mask:0xf bank_mask:0xf
	v_mov_b32_dpp v111, v90 row_shr:2 row_mask:0xf bank_mask:0xf
	v_mul_f32_e32 v113, 0xbfb8aa3b, v113
	v_mul_f32_e32 v114, 0x3fcc422a, v114
	v_mov_b32_dpp v96, v90 row_shr:1 row_mask:0xf bank_mask:0xf
	v_fma_f32 v111, v140, v111, v124
	v_exp_f32_e32 v113, v113
	v_mul_f32_e32 v114, 0xbfb8aa3b, v114
	v_fmac_f32_e32 v111, v132, v96
	v_mov_b32_dpp v112, v165 row_ror:2 row_mask:0xf bank_mask:0xf
	v_exp_f32_e32 v114, v114
	v_mov_b32_dpp v96, v165 row_ror:1 row_mask:0xf bank_mask:0xf
	v_mov_b32_dpp v112, v91 row_shr:2 row_mask:0xf bank_mask:0xf
	v_fma_f32 v112, v141, v112, v125
	v_mov_b32_dpp v96, v91 row_shr:1 row_mask:0xf bank_mask:0xf
	v_fmac_f32_e32 v112, v133, v96
	v_add_f32_e32 v96, 1.0, v113
; __device__ __forceinline__ unsigned cvt_pk_bf16(float lo, float hi) { unsigned r; asm volatile("v_cvt_pk_bf16_f32 %0, %1, %2" : "=v"(r) : "v"(lo), "v"(hi)); return r; }
; __device__ __forceinline__ float gelu_t(float x) { const float u = 1.5957691216f * (x + 0.044715f * x * x * x); return x * sigm(u); }
; __device__ __forceinline__ float dpp_shr1(float old, float src) { return __int_as_float(__builtin_amdgcn_update_dpp(__float_as_int(old), __float_as_int(src), 0x111, 0xf, 0xf, false)); }
; __device__ __forceinline__ float dpp_shr2(float old, float src) { return __int_as_float(__builtin_amdgcn_update_dpp(__float_as_int(old), __float_as_int(src), 0x112, 0xf, 0xf, false)); }
; __device__ __forceinline__ float dpp_ror1(float src) { return __int_as_float(__builtin_amdgcn_update_dpp(0, __float_as_int(src), 0x121, 0xf, 0xf, false)); }
; __device__ __forceinline__ float dpp_ror2(float src) { return __int_as_float(__builtin_amdgcn_update_dpp(0, __float_as_int(src), 0x122, 0xf, 0xf, false)); }
;     __device__ __forceinline__ void operator()(AccT& acc, const Unit& u, int wr, int wc, int fr, int fq) const {
;     ...
;                 for (int m = 0; m < 4; ++m) {
;                     f32x4 c2[2];
; #pragma unroll
;                     for (int bj = 0; bj < 2; ++bj) { const f32x4 cur = acc[ai][bj][m][n]; const f32x4 pv = (m == 0) ? hv[bj] : acc[ai][bj][m == 0 ? 0 : m - 1][n];
; #pragma unroll
;                         for (int j = 0; j < 4; ++j) { const float p1 = dpp_shr1(dpp_ror1(pv[j]), cur[j]), p2 = dpp_shr2(dpp_ror2(pv[j]), cur[j]);
;                             c2[bj][j] = bia[bj][j] + wgt[bj][0][j] * p2 + wgt[bj][1][j] * p1 + wgt[bj][2][j] * cur[j]; } }
;                     u32x2 w; w.x = cvt_pk_bf16(gelu_t(c2[0][0]) * c2[1][0], gelu_t(c2[0][1]) * c2[1][1]); w.y = cvt_pk_bf16(gelu_t(c2[0][2]) * c2[1][2], gelu_t(c2[0][3]) * c2[1][3]);
	v_rcp_f32_e32 v96, v96
	v_add_f32_e32 v113, 1.0, v114
	v_rcp_f32_e32 v113, v113
	v_fmac_f32_e32 v101, v94, v152
	v_fmac_f32_e32 v102, v95, v153
	v_fmac_f32_e32 v103, v88, v134
	v_mul_f32_e32 v96, v97, v96
	v_mul_f32_e32 v96, v96, v103
	v_mul_f32_e32 v97, v100, v113
	v_mul_f32_e32 v100, 0x3d372713, v101
	v_mul_f32_e32 v103, 0x3d372713, v102
	v_mul_f32_e32 v100, v101, v100
	v_mul_f32_e32 v103, v102, v103
	v_fma_f32 v100, v101, v100, v101
	v_fma_f32 v103, v102, v103, v102
	v_mul_f32_e32 v100, 0x3fcc422a, v100
	v_mul_f32_e32 v103, 0x3fcc422a, v103
	v_mul_f32_e32 v100, 0xbfb8aa3b, v100
	v_mul_f32_e32 v103, 0xbfb8aa3b, v103
	v_exp_f32_e32 v100, v100
	v_exp_f32_e32 v103, v103
	v_fmac_f32_e32 v110, v89, v135
	v_mul_f32_e32 v97, v97, v110
	v_add_f32_e32 v100, 1.0, v100
	v_add_f32_e32 v103, 1.0, v103
	v_rcp_f32_e32 v100, v100
	v_rcp_f32_e32 v103, v103
	v_fmac_f32_e32 v111, v90, v136
	v_fmac_f32_e32 v112, v91, v137
	v_cvt_pk_bf16_f32 v96, v96, v97
	v_mul_f32_e32 v97, v101, v100
	v_mul_f32_e32 v100, v102, v103
	v_mul_f32_e32 v97, v97, v111
	v_mul_f32_e32 v100, v100, v112
	v_mov_b32_dpp v101, v92 row_ror:2 row_mask:0xf bank_mask:0xf
	v_cvt_pk_bf16_f32 v97, v97, v100
	s_nop 0
	v_mov_b32_dpp v101, v84 row_shr:2 row_mask:0xf bank_mask:0xf
	v_mov_b32_dpp v100, v92 row_ror:1 row_mask:0xf bank_mask:0xf
	v_fma_f32 v92, v142, v101, v118
	v_mov_b32_dpp v100, v84 row_shr:1 row_mask:0xf bank_mask:0xf
	v_fmac_f32_e32 v92, v146, v100
	v_mov_b32_dpp v101, v93 row_ror:2 row_mask:0xf bank_mask:0xf
	v_fmac_f32_e32 v92, v84, v150
	v_mov_b32_dpp v101, v85 row_shr:2 row_mask:0xf bank_mask:0xf
	v_mov_b32_dpp v100, v93 row_ror:1 row_mask:0xf bank_mask:0xf
	v_fma_f32 v93, v143, v101, v119
	v_mov_b32_dpp v100, v85 row_shr:1 row_mask:0xf bank_mask:0xf
	v_fmac_f32_e32 v93, v147, v100
	v_mov_b32_dpp v101, v94 row_ror:2 row_mask:0xf bank_mask:0xf
	v_fmac_f32_e32 v93, v85, v151
	v_mov_b32_dpp v101, v86 row_shr:2 row_mask:0xf bank_mask:0xf
	v_mov_b32_dpp v100, v94 row_ror:1 row_mask:0xf bank_mask:0xf
	v_fma_f32 v94, v144, v101, v120
	v_mov_b32_dpp v100, v86 row_shr:1 row_mask:0xf bank_mask:0xf
	v_fmac_f32_e32 v94, v148, v100
	v_mov_b32_dpp v101, v95 row_ror:2 row_mask:0xf bank_mask:0xf
	v_mul_f32_e32 v102, 0x3d372713, v93
	v_mov_b32_dpp v101, v87 row_shr:2 row_mask:0xf bank_mask:0xf
	v_mov_b32_dpp v100, v95 row_ror:1 row_mask:0xf bank_mask:0xf
	v_fma_f32 v95, v145, v101, v121
	v_mov_b32_dpp v100, v87 row_shr:1 row_mask:0xf bank_mask:0xf
	v_fmac_f32_e32 v95, v149, v100
	v_mov_b32_dpp v101, v88 row_ror:2 row_mask:0xf bank_mask:0xf
	v_mul_f32_e32 v102, v93, v102
	v_mov_b32_dpp v101, v80 row_shr:2 row_mask:0xf bank_mask:0xf
	v_mov_b32_dpp v100, v88 row_ror:1 row_mask:0xf bank_mask:0xf
	v_fma_f32 v88, v138, v101, v122
	v_mov_b32_dpp v100, v80 row_shr:1 row_mask:0xf bank_mask:0xf
	v_fmac_f32_e32 v88, v130, v100
	v_mov_b32_dpp v101, v89 row_ror:2 row_mask:0xf bank_mask:0xf
	v_fma_f32 v102, v93, v102, v93
	v_mov_b32_dpp v101, v81 row_shr:2 row_mask:0xf bank_mask:0xf
	v_mov_b32_dpp v100, v89 row_ror:1 row_mask:0xf bank_mask:0xf
	v_fma_f32 v89, v139, v101, v123
	v_mov_b32_dpp v100, v81 row_shr:1 row_mask:0xf bank_mask:0xf
	v_fmac_f32_e32 v89, v131, v100
	v_mov_b32_dpp v101, v90 row_ror:2 row_mask:0xf bank_mask:0xf
	v_mul_f32_e32 v102, 0x3fcc422a, v102
	v_mov_b32_dpp v101, v82 row_shr:2 row_mask:0xf bank_mask:0xf
	v_mov_b32_dpp v100, v90 row_ror:1 row_mask:0xf bank_mask:0xf
	v_fma_f32 v90, v140, v101, v124
	v_mov_b32_dpp v100, v82 row_shr:1 row_mask:0xf bank_mask:0xf
	v_fmac_f32_e32 v90, v132, v100
	v_mov_b32_dpp v101, v91 row_ror:2 row_mask:0xf bank_mask:0xf
	v_mul_f32_e32 v102, 0xbfb8aa3b, v102
	v_mov_b32_dpp v101, v83 row_shr:2 row_mask:0xf bank_mask:0xf
	v_mov_b32_dpp v100, v91 row_ror:1 row_mask:0xf bank_mask:0xf
	v_fma_f32 v91, v141, v101, v125
	v_mul_f32_e32 v101, 0x3d372713, v92
	v_mul_f32_e32 v101, v92, v101
	v_fma_f32 v101, v92, v101, v92
	v_mul_f32_e32 v101, 0x3fcc422a, v101
	v_mul_f32_e32 v101, 0xbfb8aa3b, v101
	v_exp_f32_e32 v101, v101
	v_exp_f32_e32 v102, v102
	v_mov_b32_dpp v100, v83 row_shr:1 row_mask:0xf bank_mask:0xf
	v_fmac_f32_e32 v91, v133, v100
	v_add_f32_e32 v100, 1.0, v101
	v_rcp_f32_e32 v100, v100
	v_add_f32_e32 v101, 1.0, v102
	v_rcp_f32_e32 v101, v101
	v_fmac_f32_e32 v94, v86, v152
	v_fmac_f32_e32 v88, v80, v134
	v_mul_f32_e32 v92, v92, v100
	v_fmac_f32_e32 v95, v87, v153
	v_mul_f32_e32 v88, v92, v88
	v_mul_f32_e32 v92, v93, v101
	v_mul_f32_e32 v93, 0x3d372713, v94
	v_mul_f32_e32 v93, v94, v93
	v_mul_f32_e32 v100, 0x3d372713, v95
	v_fma_f32 v93, v94, v93, v94
	v_mul_f32_e32 v100, v95, v100
	v_mul_f32_e32 v93, 0x3fcc422a, v93
	v_fma_f32 v100, v95, v100, v95
	v_mul_f32_e32 v93, 0xbfb8aa3b, v93
	v_mul_f32_e32 v100, 0x3fcc422a, v100
	v_exp_f32_e32 v93, v93
	v_mul_f32_e32 v100, 0xbfb8aa3b, v100
	v_exp_f32_e32 v100, v100
	v_fmac_f32_e32 v89, v81, v135
	v_mul_f32_e32 v89, v92, v89
	v_add_f32_e32 v92, 1.0, v93
	v_rcp_f32_e32 v92, v92
	v_add_f32_e32 v93, 1.0, v100
	v_rcp_f32_e32 v93, v93
	v_fmac_f32_e32 v90, v82, v136
	v_cvt_pk_bf16_f32 v88, v88, v89
	v_mul_f32_e32 v89, v94, v92
	v_fmac_f32_e32 v91, v83, v137
	v_mul_f32_e32 v89, v89, v90
	v_mul_f32_e32 v90, v95, v93
	v_mul_f32_e32 v90, v90, v91
	v_cvt_pk_bf16_f32 v89, v89, v90
	s_nop 0
	v_mov_b32_dpp v91, v84 row_ror:2 row_mask:0xf bank_mask:0xf
	v_mov_b32_dpp v90, v84 row_ror:1 row_mask:0xf bank_mask:0xf
	s_nop 0
	v_mov_b32_dpp v91, v76 row_shr:2 row_mask:0xf bank_mask:0xf
	v_fma_f32 v84, v142, v91, v118
	v_mov_b32_dpp v90, v76 row_shr:1 row_mask:0xf bank_mask:0xf
	v_fmac_f32_e32 v84, v146, v90
	v_mov_b32_dpp v91, v85 row_ror:2 row_mask:0xf bank_mask:0xf
	v_fmac_f32_e32 v84, v76, v150
	v_mov_b32_dpp v91, v77 row_shr:2 row_mask:0xf bank_mask:0xf
; __device__ __forceinline__ unsigned cvt_pk_bf16(float lo, float hi) { unsigned r; asm volatile("v_cvt_pk_bf16_f32 %0, %1, %2" : "=v"(r) : "v"(lo), "v"(hi)); return r; }
; __device__ __forceinline__ float gelu_t(float x) { const float u = 1.5957691216f * (x + 0.044715f * x * x * x); return x * sigm(u); }
; __device__ __forceinline__ float dpp_shr1(float old, float src) { return __int_as_float(__builtin_amdgcn_update_dpp(__float_as_int(old), __float_as_int(src), 0x111, 0xf, 0xf, false)); }
; __device__ __forceinline__ float dpp_shr2(float old, float src) { return __int_as_float(__builtin_amdgcn_update_dpp(__float_as_int(old), __float_as_int(src), 0x112, 0xf, 0xf, false)); }
; __device__ __forceinline__ float dpp_ror1(float src) { return __int_as_float(__builtin_amdgcn_update_dpp(0, __float_as_int(src), 0x121, 0xf, 0xf, false)); }
; __device__ __forceinline__ float dpp_ror2(float src) { return __int_as_float(__builtin_amdgcn_update_dpp(0, __float_as_int(src), 0x122, 0xf, 0xf, false)); }
;     __device__ __forceinline__ void operator()(AccT& acc, const Unit& u, int wr, int wc, int fr, int fq) const {
;     ...
;                 for (int m = 0; m < 4; ++m) {
;                     f32x4 c2[2];
; #pragma unroll
;                     for (int bj = 0; bj < 2; ++bj) { const f32x4 cur = acc[ai][bj][m][n]; const f32x4 pv = (m == 0) ? hv[bj] : acc[ai][bj][m == 0 ? 0 : m - 1][n];
; #pragma unroll
;                         for (int j = 0; j < 4; ++j) { const float p1 = dpp_shr1(dpp_ror1(pv[j]), cur[j]), p2 = dpp_shr2(dpp_ror2(pv[j]), cur[j]);
;                             c2[bj][j] = bia[bj][j] + wgt[bj][0][j] * p2 + wgt[bj][1][j] * p1 + wgt[bj][2][j] * cur[j]; } }
;                     u32x2 w; w.x = cvt_pk_bf16(gelu_t(c2[0][0]) * c2[1][0], gelu_t(c2[0][1]) * c2[1][1]); w.y = cvt_pk_bf16(gelu_t(c2[0][2]) * c2[1][2], gelu_t(c2[0][3]) * c2[1][3]);
	v_mov_b32_dpp v90, v85 row_ror:1 row_mask:0xf bank_mask:0xf
	v_fma_f32 v85, v143, v91, v119
	v_mov_b32_dpp v90, v77 row_shr:1 row_mask:0xf bank_mask:0xf
	v_fmac_f32_e32 v85, v147, v90
	v_mov_b32_dpp v91, v86 row_ror:2 row_mask:0xf bank_mask:0xf
	v_fmac_f32_e32 v85, v77, v151
	v_mov_b32_dpp v91, v78 row_shr:2 row_mask:0xf bank_mask:0xf
	v_mov_b32_dpp v90, v86 row_ror:1 row_mask:0xf bank_mask:0xf
	v_fma_f32 v86, v144, v91, v120
	v_mov_b32_dpp v90, v78 row_shr:1 row_mask:0xf bank_mask:0xf
	v_fmac_f32_e32 v86, v148, v90
	v_mov_b32_dpp v91, v87 row_ror:2 row_mask:0xf bank_mask:0xf
	v_mul_f32_e32 v92, 0x3d372713, v85
	v_mov_b32_dpp v91, v79 row_shr:2 row_mask:0xf bank_mask:0xf
	v_mov_b32_dpp v90, v87 row_ror:1 row_mask:0xf bank_mask:0xf
	v_fma_f32 v87, v145, v91, v121
	v_mov_b32_dpp v90, v79 row_shr:1 row_mask:0xf bank_mask:0xf
	v_fmac_f32_e32 v87, v149, v90
	v_mov_b32_dpp v91, v80 row_ror:2 row_mask:0xf bank_mask:0xf
	v_mul_f32_e32 v92, v85, v92
	v_mov_b32_dpp v91, v68 row_shr:2 row_mask:0xf bank_mask:0xf
	v_mov_b32_dpp v90, v80 row_ror:1 row_mask:0xf bank_mask:0xf
	v_fma_f32 v80, v138, v91, v122
	v_mov_b32_dpp v90, v68 row_shr:1 row_mask:0xf bank_mask:0xf
	v_fmac_f32_e32 v80, v130, v90
	v_mov_b32_dpp v91, v81 row_ror:2 row_mask:0xf bank_mask:0xf
	v_fma_f32 v92, v85, v92, v85
	v_mov_b32_dpp v91, v69 row_shr:2 row_mask:0xf bank_mask:0xf
	v_mov_b32_dpp v90, v81 row_ror:1 row_mask:0xf bank_mask:0xf
	v_fma_f32 v81, v139, v91, v123
	v_mov_b32_dpp v90, v69 row_shr:1 row_mask:0xf bank_mask:0xf
	v_fmac_f32_e32 v81, v131, v90
	v_mov_b32_dpp v91, v82 row_ror:2 row_mask:0xf bank_mask:0xf
	v_mul_f32_e32 v92, 0x3fcc422a, v92
	v_mov_b32_dpp v91, v70 row_shr:2 row_mask:0xf bank_mask:0xf
	v_mov_b32_dpp v90, v82 row_ror:1 row_mask:0xf bank_mask:0xf
	v_fma_f32 v82, v140, v91, v124
	v_mov_b32_dpp v90, v70 row_shr:1 row_mask:0xf bank_mask:0xf
	v_fmac_f32_e32 v82, v132, v90
	v_mov_b32_dpp v91, v83 row_ror:2 row_mask:0xf bank_mask:0xf
	v_mul_f32_e32 v92, 0xbfb8aa3b, v92
	v_mov_b32_dpp v91, v71 row_shr:2 row_mask:0xf bank_mask:0xf
	v_mov_b32_dpp v90, v83 row_ror:1 row_mask:0xf bank_mask:0xf
	v_fma_f32 v83, v141, v91, v125
	v_mul_f32_e32 v91, 0x3d372713, v84
	v_mul_f32_e32 v91, v84, v91
	v_fma_f32 v91, v84, v91, v84
	v_mul_f32_e32 v91, 0x3fcc422a, v91
	v_mul_f32_e32 v91, 0xbfb8aa3b, v91
	v_exp_f32_e32 v91, v91
	v_exp_f32_e32 v92, v92
	v_mov_b32_dpp v90, v71 row_shr:1 row_mask:0xf bank_mask:0xf
	v_fmac_f32_e32 v83, v133, v90
	v_add_f32_e32 v90, 1.0, v91
	v_rcp_f32_e32 v90, v90
	v_add_f32_e32 v91, 1.0, v92
	v_rcp_f32_e32 v91, v91
	v_fmac_f32_e32 v86, v78, v152
	v_fmac_f32_e32 v80, v68, v134
	v_mul_f32_e32 v84, v84, v90
	v_fmac_f32_e32 v87, v79, v153
	v_mul_f32_e32 v80, v84, v80
	v_mul_f32_e32 v84, v85, v91
	v_mul_f32_e32 v85, 0x3d372713, v86
	v_mul_f32_e32 v85, v86, v85
	v_mul_f32_e32 v90, 0x3d372713, v87
	v_fma_f32 v85, v86, v85, v86
	v_mul_f32_e32 v90, v87, v90
	v_mul_f32_e32 v85, 0x3fcc422a, v85
	v_fma_f32 v90, v87, v90, v87
	v_mul_f32_e32 v85, 0xbfb8aa3b, v85
	v_mul_f32_e32 v90, 0x3fcc422a, v90
	v_exp_f32_e32 v85, v85
	v_mul_f32_e32 v90, 0xbfb8aa3b, v90
	v_exp_f32_e32 v90, v90
	v_fmac_f32_e32 v81, v69, v135
	v_mul_f32_e32 v81, v84, v81
	v_add_f32_e32 v84, 1.0, v85
	v_rcp_f32_e32 v84, v84
	v_add_f32_e32 v85, 1.0, v90
	v_rcp_f32_e32 v85, v85
	v_fmac_f32_e32 v82, v70, v136
	v_cvt_pk_bf16_f32 v80, v80, v81
	v_mul_f32_e32 v81, v86, v84
	v_fmac_f32_e32 v83, v71, v137
	v_mul_f32_e32 v81, v81, v82
	v_mul_f32_e32 v82, v87, v85
	v_mul_f32_e32 v82, v82, v83
	v_cvt_pk_bf16_f32 v81, v81, v82
	v_mov_b32_e32 v90, 0
	v_mov_b32_dpp v83, v76 row_ror:2 row_mask:0xf bank_mask:0xf
	v_mov_b32_dpp v82, v76 row_ror:1 row_mask:0xf bank_mask:0xf
	s_nop 0
	v_mov_b32_dpp v83, v72 row_shr:2 row_mask:0xf bank_mask:0xf
	v_mov_b32_dpp v82, v72 row_shr:1 row_mask:0xf bank_mask:0xf
	v_fma_f32 v76, v142, v83, v118
	v_fmac_f32_e32 v76, v146, v82
	v_fmac_f32_e32 v76, v72, v150
	v_mov_b32_dpp v82, v77 row_ror:2 row_mask:0xf bank_mask:0xf
	v_mov_b32_e32 v118, 0
	v_mov_b32_dpp v72, v77 row_ror:1 row_mask:0xf bank_mask:0xf
	v_mov_b32_dpp v82, v73 row_shr:2 row_mask:0xf bank_mask:0xf
	v_fma_f32 v77, v143, v82, v119
	v_mov_b32_dpp v72, v73 row_shr:1 row_mask:0xf bank_mask:0xf
	v_fmac_f32_e32 v77, v147, v72
	v_fmac_f32_e32 v77, v73, v151
	v_mov_b32_e32 v119, 0
	v_mov_b32_dpp v73, v78 row_ror:2 row_mask:0xf bank_mask:0xf
	v_mov_b32_dpp v72, v78 row_ror:1 row_mask:0xf bank_mask:0xf
	s_nop 0
	v_mov_b32_dpp v73, v74 row_shr:2 row_mask:0xf bank_mask:0xf
	v_mov_b32_dpp v72, v74 row_shr:1 row_mask:0xf bank_mask:0xf
	v_fma_f32 v73, v144, v73, v120
	v_fmac_f32_e32 v73, v148, v72
	v_fmac_f32_e32 v73, v74, v152
	v_mov_b32_e32 v120, 0
	v_mov_b32_dpp v74, v79 row_ror:2 row_mask:0xf bank_mask:0xf
	v_mov_b32_dpp v72, v79 row_ror:1 row_mask:0xf bank_mask:0xf
	s_nop 0
	v_mov_b32_dpp v74, v75 row_shr:2 row_mask:0xf bank_mask:0xf
	v_mov_b32_dpp v72, v75 row_shr:1 row_mask:0xf bank_mask:0xf
	v_fmac_f32_e32 v121, v145, v74
	v_fmac_f32_e32 v121, v149, v72
	v_mov_b32_dpp v74, v68 row_ror:2 row_mask:0xf bank_mask:0xf
	v_fmac_f32_e32 v121, v75, v153
	v_mov_b32_dpp v72, v68 row_ror:1 row_mask:0xf bank_mask:0xf
	v_mov_b32_dpp v74, v64 row_shr:2 row_mask:0xf bank_mask:0xf
	v_fma_f32 v68, v138, v74, v122
	v_mov_b32_dpp v72, v64 row_shr:1 row_mask:0xf bank_mask:0xf
	v_fmac_f32_e32 v68, v130, v72
	v_fmac_f32_e32 v68, v64, v134
	v_mov_b32_dpp v72, v69 row_ror:2 row_mask:0xf bank_mask:0xf
	v_mov_b32_e32 v122, 0
	v_mov_b32_dpp v64, v69 row_ror:1 row_mask:0xf bank_mask:0xf
	v_mov_b32_dpp v72, v65 row_shr:2 row_mask:0xf bank_mask:0xf
	v_fma_f32 v69, v139, v72, v123
	v_mov_b32_dpp v64, v65 row_shr:1 row_mask:0xf bank_mask:0xf
; #define LAS __attribute__((address_space(3)))
; __device__ __forceinline__ float dpp_shr1(float old, float src) { return __int_as_float(__builtin_amdgcn_update_dpp(__float_as_int(old), __float_as_int(src), 0x111, 0xf, 0xf, false)); }
; __device__ __forceinline__ float dpp_shr2(float old, float src) { return __int_as_float(__builtin_amdgcn_update_dpp(__float_as_int(old), __float_as_int(src), 0x112, 0xf, 0xf, false)); }
; __device__ __forceinline__ float dpp_ror1(float src) { return __int_as_float(__builtin_amdgcn_update_dpp(0, __float_as_int(src), 0x121, 0xf, 0xf, false)); }
; __device__ __forceinline__ float dpp_ror2(float src) { return __int_as_float(__builtin_amdgcn_update_dpp(0, __float_as_int(src), 0x122, 0xf, 0xf, false)); }
;     __device__ __forceinline__ int xidx(int ai, int w_r, int wc, int rsel, int fq, int bj, int n) const { return (((((ai * 2 + w_r) * 4 + wc) * 2 + rsel) * 4 + fq) * 4 + bj * 2 + n) * 16; }
;     __device__ __forceinline__ void operator()(AccT& acc, const Unit& u, int wr, int wc, int fr, int fq) const {
;     ...
;             const int cg = u.pn * 128 + lcol + 4 * n;
;             f32x4 wgt[2][3], bia[2];
; #pragma unroll
;             for (int bj = 0; bj < 2; ++bj) { const int ch = cg + bj * FF; bia[bj] = *(const f32x4*)(cb + ch);
; #pragma unroll
;                 for (int k = 0; k < 3; ++k) wgt[bj][k] = *(const f32x4*)(cw + (size_t)k * FF2 + ch); }
; #pragma unroll
;             for (int ai = 0; ai < 2; ++ai) {
;                 f32x4 hv[2]; hv[0] = (f32x4){0.f, 0.f, 0.f, 0.f}; hv[1] = hv[0];
;                 const bool has_pred = (wr == 1) || (ai == 1);
;                 const int pa = (wr == 1) ? ai : 0, pw = (wr == 1) ? 0 : 1;
;                 if (has_pred && fr >= 14) { hv[0] = *(const LAS f32x4*)(xl + xidx(pa, pw, wc, fr - 14, fq, 0, n)); hv[1] = *(const LAS f32x4*)(xl + xidx(pa, pw, wc, fr - 14, fq, 1, n)); }
;     ...
;                     for (int bj = 0; bj < 2; ++bj) { const f32x4 cur = acc[ai][bj][m][n]; const f32x4 pv = (m == 0) ? hv[bj] : acc[ai][bj][m == 0 ? 0 : m - 1][n];
; #pragma unroll
;                         for (int j = 0; j < 4; ++j) { const float p1 = dpp_shr1(dpp_ror1(pv[j]), cur[j]), p2 = dpp_shr2(dpp_ror2(pv[j]), cur[j]);
;                             c2[bj][j] = bia[bj][j] + wgt[bj][0][j] * p2 + wgt[bj][1][j] * p1 + wgt[bj][2][j] * cur[j]; } }
	v_fmac_f32_e32 v69, v131, v64
	v_fmac_f32_e32 v69, v65, v135
	v_mov_b32_e32 v123, 0
	v_mov_b32_dpp v65, v70 row_ror:2 row_mask:0xf bank_mask:0xf
	v_mov_b32_dpp v64, v70 row_ror:1 row_mask:0xf bank_mask:0xf
	v_mul_f32_e32 v70, 0x3d372713, v77
	v_mov_b32_dpp v65, v66 row_shr:2 row_mask:0xf bank_mask:0xf
	v_mov_b32_dpp v64, v66 row_shr:1 row_mask:0xf bank_mask:0xf
	v_fma_f32 v65, v140, v65, v124
	v_fmac_f32_e32 v65, v132, v64
	v_fmac_f32_e32 v65, v66, v136
	v_mul_f32_e32 v70, v77, v70
	v_mov_b32_dpp v66, v71 row_ror:2 row_mask:0xf bank_mask:0xf
	v_mov_b32_dpp v64, v71 row_ror:1 row_mask:0xf bank_mask:0xf
	v_fma_f32 v70, v77, v70, v77
	v_mov_b32_dpp v66, v67 row_shr:2 row_mask:0xf bank_mask:0xf
	v_fmac_f32_e32 v125, v141, v66
	v_mul_f32_e32 v66, 0x3d372713, v76
	v_mul_f32_e32 v66, v76, v66
	v_fma_f32 v66, v76, v66, v76
	v_mul_f32_e32 v66, 0x3fcc422a, v66
	v_mul_f32_e32 v66, 0xbfb8aa3b, v66
	v_exp_f32_e32 v66, v66
	v_mov_b32_dpp v64, v67 row_shr:1 row_mask:0xf bank_mask:0xf
	v_fmac_f32_e32 v125, v133, v64
	v_fmac_f32_e32 v125, v67, v137
	v_add_f32_e32 v64, 1.0, v66
	v_rcp_f32_e32 v64, v64
	v_mul_f32_e32 v67, 0x3d372713, v73
	v_mul_f32_e32 v70, 0x3fcc422a, v70
	v_mul_f32_e32 v67, v73, v67
	v_mul_f32_e32 v64, v76, v64
	v_mul_f32_e32 v64, v64, v68
	v_mul_f32_e32 v68, 0x3d372713, v121
	v_mul_f32_e32 v70, 0xbfb8aa3b, v70
	v_fma_f32 v67, v73, v67, v73
	v_mul_f32_e32 v68, v121, v68
	v_exp_f32_e32 v70, v70
	v_mul_f32_e32 v67, 0x3fcc422a, v67
	v_fma_f32 v68, v121, v68, v121
	v_mul_f32_e32 v67, 0xbfb8aa3b, v67
	v_mul_f32_e32 v68, 0x3fcc422a, v68
	v_exp_f32_e32 v67, v67
	v_mul_f32_e32 v68, 0xbfb8aa3b, v68
	v_exp_f32_e32 v68, v68
	v_add_f32_e32 v66, 1.0, v70
	v_rcp_f32_e32 v66, v66
	v_add_f32_e32 v67, 1.0, v67
	v_rcp_f32_e32 v67, v67
	v_add_f32_e32 v68, 1.0, v68
	v_rcp_f32_e32 v68, v68
	v_mul_f32_e32 v66, v77, v66
	v_mul_f32_e32 v66, v66, v69
	v_cvt_pk_bf16_f32 v64, v64, v66
	v_mul_f32_e32 v66, v73, v67
	v_mul_f32_e32 v65, v66, v65
	v_mul_f32_e32 v66, v121, v68
	v_mul_f32_e32 v66, v66, v125
	v_cvt_pk_bf16_f32 v65, v65, v66
	v_add_co_u32_e32 v66, vcc, 0x15000, v188
	v_mov_b32_e32 v100, v200
	v_mov_b32_e32 v101, v201
	v_mov_b32_e32 v102, v202
	v_mov_b32_e32 v103, v203
	s_nop 0
	v_addc_co_u32_e32 v67, vcc, 0, v189, vcc
	v_mov_b32_e32 v114, v204
	v_mov_b32_e32 v115, v205
	v_mov_b32_e32 v116, v206
	v_mov_b32_e32 v117, v207
	v_mov_b32_e32 v110, v208
	v_mov_b32_e32 v111, v209
	v_mov_b32_e32 v112, v210
	v_mov_b32_e32 v113, v211
	v_add_co_u32_e32 v66, vcc, 0x2b000, v188
	v_mov_b32_e32 v121, 0
	s_nop 0
	v_addc_co_u32_e32 v67, vcc, 0, v189, vcc
	v_mov_b32_e32 v92, v212
	v_mov_b32_e32 v93, v213
	v_mov_b32_e32 v94, v214
	v_mov_b32_e32 v95, v215
	v_add_co_u32_e32 v66, vcc, 0xa000, v190
	v_mov_b32_e32 v124, 0
	s_nop 0
	v_addc_co_u32_e32 v67, vcc, 0, v191, vcc
	v_mov_b32_e32 v70, v216
	v_mov_b32_e32 v71, v217
	v_mov_b32_e32 v72, v218
	v_mov_b32_e32 v73, v219
	v_add_co_u32_e32 v66, vcc, 0xa000, v188
	v_mov_b32_e32 v125, 0
	s_nop 0
	v_addc_co_u32_e32 v67, vcc, 0, v189, vcc
	v_add_co_u32_e32 v68, vcc, 0x20000, v188
	s_nop 1
	v_addc_co_u32_e32 v69, vcc, 0, v189, vcc
	v_mov_b32_e32 v74, v220
	v_mov_b32_e32 v75, v221
	v_mov_b32_e32 v76, v222
	v_mov_b32_e32 v77, v223
	v_mov_b32_e32 v84, v224
	v_mov_b32_e32 v85, v225
	v_mov_b32_e32 v86, v226
	v_mov_b32_e32 v87, v227
	v_add_co_u32_e32 v66, vcc, 0x35000, v188
	s_nop 1
	v_addc_co_u32_e32 v67, vcc, 0, v189, vcc
	v_mov_b32_e32 v66, v228
	v_mov_b32_e32 v67, v229
	v_mov_b32_e32 v68, v230
	v_mov_b32_e32 v69, v231
	s_and_saveexec_b64 s[16:17], s[12:13]
	s_cbranch_execz .LBB0_792
	ds_read_b128 v[122:125], v184 offset:16
	ds_read_b128 v[118:121], v184 offset:48
.LBB0_792:
	s_or_b64 exec, exec, s[16:17]
	s_waitcnt lgkmcnt(1)
	v_mov_b32_dpp v126, v122 row_ror:2 row_mask:0xf bank_mask:0xf
	s_waitcnt lgkmcnt(0)
	v_mov_b32_dpp v127, v118 row_ror:2 row_mask:0xf bank_mask:0xf
	v_mov_b32_dpp v82, v122 row_ror:1 row_mask:0xf bank_mask:0xf
	v_mov_b32_dpp v126, v60 row_shr:2 row_mask:0xf bank_mask:0xf
	v_mov_b32_dpp v128, v123 row_ror:1 row_mask:0xf bank_mask:0xf
	v_mov_b32_dpp v130, v123 row_ror:2 row_mask:0xf bank_mask:0xf
	v_mov_b32_dpp v83, v118 row_ror:1 row_mask:0xf bank_mask:0xf
	v_mov_b32_dpp v127, v56 row_shr:2 row_mask:0xf bank_mask:0xf
	s_waitcnt vmcnt(6)
	v_mov_b32_e32 v78, v114
	s_waitcnt vmcnt(2)
	v_mov_b32_e32 v79, v74
	v_mov_b32_e32 v122, v100
	v_mov_b32_e32 v123, v70
	v_mov_b32_dpp v82, v60 row_shr:1 row_mask:0xf bank_mask:0xf
	v_mov_b32_dpp v134, v124 row_ror:1 row_mask:0xf bank_mask:0xf
	v_mov_b32_dpp v136, v124 row_ror:2 row_mask:0xf bank_mask:0xf
	v_mov_b32_dpp v138, v125 row_ror:1 row_mask:0xf bank_mask:0xf
	v_mov_b32_dpp v140, v125 row_ror:2 row_mask:0xf bank_mask:0xf
	v_mov_b32_dpp v83, v56 row_shr:1 row_mask:0xf bank_mask:0xf
	v_pk_fma_f32 v[126:127], v[78:79], v[126:127], v[122:123]
	v_mov_b32_e32 v124, v110
	s_waitcnt vmcnt(1)
	v_mov_b32_e32 v125, v84
	v_pk_fma_f32 v[82:83], v[124:125], v[82:83], v[126:127]
	v_mov_b32_e32 v142, v60
	v_mov_b32_e32 v143, v56
	v_mov_b32_e32 v126, v92
	s_waitcnt vmcnt(0)
; __device__ __forceinline__ unsigned cvt_pk_bf16(float lo, float hi) { unsigned r; asm volatile("v_cvt_pk_bf16_f32 %0, %1, %2" : "=v"(r) : "v"(lo), "v"(hi)); return r; }
; __device__ __forceinline__ float gelu_t(float x) { const float u = 1.5957691216f * (x + 0.044715f * x * x * x); return x * sigm(u); }
; __device__ __forceinline__ float dpp_shr1(float old, float src) { return __int_as_float(__builtin_amdgcn_update_dpp(__float_as_int(old), __float_as_int(src), 0x111, 0xf, 0xf, false)); }
; __device__ __forceinline__ float dpp_shr2(float old, float src) { return __int_as_float(__builtin_amdgcn_update_dpp(__float_as_int(old), __float_as_int(src), 0x112, 0xf, 0xf, false)); }
; __device__ __forceinline__ float dpp_ror1(float src) { return __int_as_float(__builtin_amdgcn_update_dpp(0, __float_as_int(src), 0x121, 0xf, 0xf, false)); }
; __device__ __forceinline__ float dpp_ror2(float src) { return __int_as_float(__builtin_amdgcn_update_dpp(0, __float_as_int(src), 0x122, 0xf, 0xf, false)); }
;     __device__ __forceinline__ void operator()(AccT& acc, const Unit& u, int wr, int wc, int fr, int fq) const {
;     ...
;                     for (int bj = 0; bj < 2; ++bj) { const f32x4 cur = acc[ai][bj][m][n]; const f32x4 pv = (m == 0) ? hv[bj] : acc[ai][bj][m == 0 ? 0 : m - 1][n];
; #pragma unroll
;                         for (int j = 0; j < 4; ++j) { const float p1 = dpp_shr1(dpp_ror1(pv[j]), cur[j]), p2 = dpp_shr2(dpp_ror2(pv[j]), cur[j]);
;                             c2[bj][j] = bia[bj][j] + wgt[bj][0][j] * p2 + wgt[bj][1][j] * p1 + wgt[bj][2][j] * cur[j]; } }
;                     u32x2 w; w.x = cvt_pk_bf16(gelu_t(c2[0][0]) * c2[1][0], gelu_t(c2[0][1]) * c2[1][1]); w.y = cvt_pk_bf16(gelu_t(c2[0][2]) * c2[1][2], gelu_t(c2[0][3]) * c2[1][3]);
;                     if (n == 0) pend[ai][m] = w;
;                     else { u32x4 w4; w4.x = pend[ai][m].x; w4.y = pend[ai][m].y; w4.z = w.x; w4.w = w.y;
;                         *(u32x4*)(F + (size_t)(t0 + ai * 128 + wr * 64 + m * 16 + fr) * FF + cg - 4) = w4; }
	v_mov_b32_e32 v127, v66
	v_mov_b32_dpp v131, v119 row_ror:2 row_mask:0xf bank_mask:0xf
	v_mov_b32_dpp v130, v61 row_shr:2 row_mask:0xf bank_mask:0xf
	v_pk_fma_f32 v[82:83], v[142:143], v[126:127], v[82:83]
	v_mov_b32_dpp v131, v57 row_shr:2 row_mask:0xf bank_mask:0xf
	v_mov_b32_e32 v74, v115
	v_mov_b32_e32 v70, v101
	v_pk_fma_f32 v[100:101], v[74:75], v[130:131], v[70:71]
	v_mov_b32_e32 v131, v68
	v_mul_f32_e32 v68, 0x3d372713, v82
	v_mov_b32_dpp v129, v119 row_ror:1 row_mask:0xf bank_mask:0xf
	v_mul_f32_e32 v68, v82, v68
	v_mov_b32_dpp v128, v61 row_shr:1 row_mask:0xf bank_mask:0xf
	v_mov_b32_dpp v129, v57 row_shr:1 row_mask:0xf bank_mask:0xf
	v_mov_b32_e32 v84, v111
	v_fma_f32 v68, v82, v68, v82
	v_pk_fma_f32 v[100:101], v[84:85], v[128:129], v[100:101]
	v_mov_b32_e32 v110, v61
	v_mov_b32_e32 v111, v57
	v_mov_b32_e32 v66, v93
	v_mul_f32_e32 v68, 0x3fcc422a, v68
	v_pk_fma_f32 v[92:93], v[110:111], v[66:67], v[100:101]
	v_mul_f32_e32 v68, 0xbfb8aa3b, v68
	v_exp_f32_e32 v91, v68
	v_mul_f32_e32 v68, 0x3d372713, v92
	v_mul_f32_e32 v68, v92, v68
	v_fma_f32 v68, v92, v68, v92
	v_mul_f32_e32 v68, 0x3fcc422a, v68
	v_mul_f32_e32 v68, 0xbfb8aa3b, v68
	v_mov_b32_e32 v130, v94
	v_exp_f32_e32 v94, v68
	v_mov_b32_dpp v137, v120 row_ror:2 row_mask:0xf bank_mask:0xf
	v_add_f32_e32 v91, 1.0, v91
	v_mov_b32_dpp v136, v62 row_shr:2 row_mask:0xf bank_mask:0xf
	v_mov_b32_dpp v135, v120 row_ror:1 row_mask:0xf bank_mask:0xf
	v_mov_b32_dpp v137, v58 row_shr:2 row_mask:0xf bank_mask:0xf
	v_mov_b32_e32 v114, v116
	v_mov_b32_e32 v115, v76
	v_mov_b32_e32 v118, v102
	v_mov_b32_e32 v119, v72
	v_mov_b32_dpp v141, v121 row_ror:2 row_mask:0xf bank_mask:0xf
	v_rcp_f32_e32 v91, v91
	v_add_f32_e32 v94, 1.0, v94
	v_mov_b32_dpp v134, v62 row_shr:1 row_mask:0xf bank_mask:0xf
	v_mov_b32_dpp v140, v63 row_shr:2 row_mask:0xf bank_mask:0xf
	v_mov_b32_dpp v135, v58 row_shr:1 row_mask:0xf bank_mask:0xf
	v_pk_fma_f32 v[100:101], v[114:115], v[136:137], v[118:119]
	v_mov_b32_e32 v128, v112
	v_mov_b32_e32 v129, v86
	v_mov_b32_dpp v139, v121 row_ror:1 row_mask:0xf bank_mask:0xf
	v_mov_b32_dpp v141, v59 row_shr:2 row_mask:0xf bank_mask:0xf
	v_mov_b32_e32 v76, v117
	v_mov_b32_e32 v72, v103
	v_rcp_f32_e32 v112, v94
	v_mov_b32_dpp v138, v63 row_shr:1 row_mask:0xf bank_mask:0xf
	v_pk_fma_f32 v[100:101], v[128:129], v[134:135], v[100:101]
	v_mov_b32_e32 v110, v62
	v_mov_b32_e32 v111, v58
	v_mov_b32_dpp v139, v59 row_shr:1 row_mask:0xf bank_mask:0xf
	v_pk_fma_f32 v[102:103], v[76:77], v[140:141], v[72:73]
	v_mov_b32_e32 v86, v113
	v_pk_fma_f32 v[100:101], v[110:111], v[130:131], v[100:101]
	v_pk_fma_f32 v[102:103], v[86:87], v[138:139], v[102:103]
	v_mov_b32_e32 v110, v63
	v_mov_b32_e32 v111, v59
	v_mov_b32_e32 v68, v95
	v_pk_fma_f32 v[94:95], v[110:111], v[68:69], v[102:103]
	v_mul_f32_e32 v82, v82, v91
	v_mul_f32_e32 v82, v82, v83
	v_mul_f32_e32 v83, v92, v112
	v_mul_f32_e32 v91, 0x3d372713, v100
	v_mul_f32_e32 v92, 0x3d372713, v94
	v_mul_f32_e32 v91, v100, v91
	v_mul_f32_e32 v92, v94, v92
	v_fma_f32 v91, v100, v91, v100
	v_fma_f32 v92, v94, v92, v94
	v_mul_f32_e32 v91, 0x3fcc422a, v91
	v_mul_f32_e32 v92, 0x3fcc422a, v92
	v_mul_f32_e32 v91, 0xbfb8aa3b, v91
	v_mul_f32_e32 v92, 0xbfb8aa3b, v92
	v_exp_f32_e32 v91, v91
	v_exp_f32_e32 v92, v92
	v_mul_f32_e32 v83, v83, v93
	s_lshl_b32 s3, s50, 8
	v_add_f32_e32 v91, 1.0, v91
	v_add_f32_e32 v92, 1.0, v92
	v_rcp_f32_e32 v91, v91
	v_rcp_f32_e32 v92, v92
	v_cvt_pk_bf16_f32 v110, v82, v83
	s_add_i32 s3, s3, s76
	v_mul_f32_e32 v82, v100, v91
	v_mul_f32_e32 v83, v94, v92
	v_mul_f32_e32 v82, v82, v101
	v_mul_f32_e32 v83, v83, v95
	v_or_b32_e32 v132, s3, v199
	v_cvt_pk_bf16_f32 v111, v82, v83
	v_mov_b64_e32 v[82:83], s[36:37]
	v_mad_i64_i32 v[92:93], s[8:9], v132, s94, v[82:83]
	v_lshlrev_b64 v[94:95], 1, v[186:187]
	v_lshl_add_u64 v[92:93], v[92:93], 0, v[94:95]
	global_store_dwordx4 v[92:93], v[108:111], off
	v_mov_b32_dpp v100, v60 row_ror:2 row_mask:0xf bank_mask:0xf
	v_mov_b32_dpp v101, v56 row_ror:2 row_mask:0xf bank_mask:0xf
	v_mov_b32_dpp v92, v60 row_ror:1 row_mask:0xf bank_mask:0xf
	v_mov_b32_dpp v100, v52 row_shr:2 row_mask:0xf bank_mask:0xf
	v_mov_b32_dpp v108, v62 row_ror:1 row_mask:0xf bank_mask:0xf
	v_mov_b32_dpp v110, v62 row_ror:2 row_mask:0xf bank_mask:0xf
	v_mov_b32_dpp v93, v56 row_ror:1 row_mask:0xf bank_mask:0xf
	v_mov_b32_dpp v101, v48 row_shr:2 row_mask:0xf bank_mask:0xf
	v_mov_b32_dpp v92, v52 row_shr:1 row_mask:0xf bank_mask:0xf
	v_mov_b32_dpp v62, v63 row_ror:1 row_mask:0xf bank_mask:0xf
	v_mov_b32_dpp v112, v63 row_ror:2 row_mask:0xf bank_mask:0xf
	v_mov_b32_dpp v93, v48 row_shr:1 row_mask:0xf bank_mask:0xf
	v_pk_fma_f32 v[100:101], v[78:79], v[100:101], v[122:123]
	v_mov_b32_dpp v113, v59 row_ror:2 row_mask:0xf bank_mask:0xf
	v_mov_b32_dpp v112, v55 row_shr:2 row_mask:0xf bank_mask:0xf
	v_pk_fma_f32 v[92:93], v[124:125], v[92:93], v[100:101]
	v_mov_b32_e32 v100, v52
	v_mov_b32_e32 v101, v48
	v_mov_b32_dpp v63, v59 row_ror:1 row_mask:0xf bank_mask:0xf
	v_mov_b32_dpp v113, v51 row_shr:2 row_mask:0xf bank_mask:0xf
	v_mov_b32_dpp v62, v55 row_shr:1 row_mask:0xf bank_mask:0xf
	v_pk_fma_f32 v[92:93], v[100:101], v[126:127], v[92:93]
	v_mov_b32_dpp v109, v58 row_ror:1 row_mask:0xf bank_mask:0xf
	v_mov_b32_dpp v111, v58 row_ror:2 row_mask:0xf bank_mask:0xf
	v_mov_b32_dpp v63, v51 row_shr:1 row_mask:0xf bank_mask:0xf
	v_pk_fma_f32 v[58:59], v[76:77], v[112:113], v[72:73]
	v_pk_fma_f32 v[58:59], v[86:87], v[62:63], v[58:59]
	v_mul_f32_e32 v63, 0x3d372713, v92
	v_mul_f32_e32 v63, v92, v63
	v_mov_b32_dpp v60, v61 row_ror:1 row_mask:0xf bank_mask:0xf
	v_mov_b32_dpp v102, v61 row_ror:2 row_mask:0xf bank_mask:0xf
; __device__ __forceinline__ unsigned cvt_pk_bf16(float lo, float hi) { unsigned r; asm volatile("v_cvt_pk_bf16_f32 %0, %1, %2" : "=v"(r) : "v"(lo), "v"(hi)); return r; }
; __device__ __forceinline__ float gelu_t(float x) { const float u = 1.5957691216f * (x + 0.044715f * x * x * x); return x * sigm(u); }
; __device__ __forceinline__ float dpp_shr1(float old, float src) { return __int_as_float(__builtin_amdgcn_update_dpp(__float_as_int(old), __float_as_int(src), 0x111, 0xf, 0xf, false)); }
; __device__ __forceinline__ float dpp_shr2(float old, float src) { return __int_as_float(__builtin_amdgcn_update_dpp(__float_as_int(old), __float_as_int(src), 0x112, 0xf, 0xf, false)); }
; __device__ __forceinline__ float dpp_ror1(float src) { return __int_as_float(__builtin_amdgcn_update_dpp(0, __float_as_int(src), 0x121, 0xf, 0xf, false)); }
; __device__ __forceinline__ float dpp_ror2(float src) { return __int_as_float(__builtin_amdgcn_update_dpp(0, __float_as_int(src), 0x122, 0xf, 0xf, false)); }
;     __device__ __forceinline__ void operator()(AccT& acc, const Unit& u, int wr, int wc, int fr, int fq) const {
;     ...
;                 for (int m = 0; m < 4; ++m) {
;                     f32x4 c2[2];
; #pragma unroll
;                     for (int bj = 0; bj < 2; ++bj) { const f32x4 cur = acc[ai][bj][m][n]; const f32x4 pv = (m == 0) ? hv[bj] : acc[ai][bj][m == 0 ? 0 : m - 1][n];
; #pragma unroll
;                         for (int j = 0; j < 4; ++j) { const float p1 = dpp_shr1(dpp_ror1(pv[j]), cur[j]), p2 = dpp_shr2(dpp_ror2(pv[j]), cur[j]);
;                             c2[bj][j] = bia[bj][j] + wgt[bj][0][j] * p2 + wgt[bj][1][j] * p1 + wgt[bj][2][j] * cur[j]; } }
;                     u32x2 w; w.x = cvt_pk_bf16(gelu_t(c2[0][0]) * c2[1][0], gelu_t(c2[0][1]) * c2[1][1]); w.y = cvt_pk_bf16(gelu_t(c2[0][2]) * c2[1][2], gelu_t(c2[0][3]) * c2[1][3]);
;                     if (n == 0) pend[ai][m] = w;
;                     else { u32x4 w4; w4.x = pend[ai][m].x; w4.y = pend[ai][m].y; w4.z = w.x; w4.w = w.y;
;                         *(u32x4*)(F + (size_t)(t0 + ai * 128 + wr * 64 + m * 16 + fr) * FF + cg - 4) = w4; }
	v_mov_b32_dpp v103, v57 row_ror:2 row_mask:0xf bank_mask:0xf
	v_fma_f32 v63, v92, v63, v92
	v_mov_b32_dpp v102, v53 row_shr:2 row_mask:0xf bank_mask:0xf
	v_mov_b32_dpp v61, v57 row_ror:1 row_mask:0xf bank_mask:0xf
	v_mov_b32_dpp v103, v49 row_shr:2 row_mask:0xf bank_mask:0xf
	v_mul_f32_e32 v63, 0x3fcc422a, v63
	v_mov_b32_dpp v60, v53 row_shr:1 row_mask:0xf bank_mask:0xf
	v_mov_b32_dpp v61, v49 row_shr:1 row_mask:0xf bank_mask:0xf
	v_pk_fma_f32 v[56:57], v[74:75], v[102:103], v[70:71]
	v_mul_f32_e32 v63, 0xbfb8aa3b, v63
	v_pk_fma_f32 v[56:57], v[84:85], v[60:61], v[56:57]
	v_mov_b32_e32 v60, v53
	v_mov_b32_e32 v61, v49
	v_exp_f32_e32 v91, v63
	v_pk_fma_f32 v[56:57], v[60:61], v[66:67], v[56:57]
	v_mov_b32_dpp v110, v54 row_shr:2 row_mask:0xf bank_mask:0xf
	v_mul_f32_e32 v63, 0x3d372713, v56
	v_mul_f32_e32 v63, v56, v63
	v_mov_b32_dpp v111, v50 row_shr:2 row_mask:0xf bank_mask:0xf
	v_fma_f32 v63, v56, v63, v56
	v_add_f32_e32 v91, 1.0, v91
	v_mov_b32_dpp v108, v54 row_shr:1 row_mask:0xf bank_mask:0xf
	v_mov_b32_dpp v109, v50 row_shr:1 row_mask:0xf bank_mask:0xf
	v_pk_fma_f32 v[60:61], v[114:115], v[110:111], v[118:119]
	v_mul_f32_e32 v63, 0x3fcc422a, v63
	v_rcp_f32_e32 v91, v91
	v_pk_fma_f32 v[60:61], v[128:129], v[108:109], v[60:61]
	v_mov_b32_e32 v100, v54
	v_mov_b32_e32 v101, v50
	v_mul_f32_e32 v63, 0xbfb8aa3b, v63
	v_pk_fma_f32 v[60:61], v[100:101], v[130:131], v[60:61]
	v_mov_b32_e32 v62, v55
	v_exp_f32_e32 v100, v63
	v_mov_b32_e32 v63, v51
	v_pk_fma_f32 v[58:59], v[62:63], v[68:69], v[58:59]
	v_mul_f32_e32 v63, 0x3d372713, v60
	v_mul_f32_e32 v62, v92, v91
	v_mul_f32_e32 v63, v60, v63
	v_mul_f32_e32 v91, 0x3d372713, v58
	v_fma_f32 v63, v60, v63, v60
	v_mul_f32_e32 v91, v58, v91
	v_add_f32_e32 v100, 1.0, v100
	v_mul_f32_e32 v63, 0x3fcc422a, v63
	v_fma_f32 v91, v58, v91, v58
	v_rcp_f32_e32 v100, v100
	v_mul_f32_e32 v63, 0xbfb8aa3b, v63
	v_mul_f32_e32 v91, 0x3fcc422a, v91
	v_exp_f32_e32 v63, v63
	v_mul_f32_e32 v91, 0xbfb8aa3b, v91
	v_exp_f32_e32 v91, v91
	v_mul_f32_e32 v56, v56, v100
	v_mul_f32_e32 v56, v56, v57
	v_add_f32_e32 v57, 1.0, v63
	v_rcp_f32_e32 v57, v57
	v_add_f32_e32 v63, 1.0, v91
	v_rcp_f32_e32 v63, v63
	v_mul_f32_e32 v62, v62, v93
	v_cvt_pk_bf16_f32 v108, v62, v56
	v_mul_f32_e32 v56, v60, v57
	v_mul_f32_e32 v56, v56, v61
	v_mul_f32_e32 v57, v58, v63
	v_mul_f32_e32 v57, v57, v59
	v_cvt_pk_bf16_f32 v109, v56, v57
	v_or_b32_e32 v56, 16, v132
	v_mad_i64_i32 v[56:57], s[8:9], v56, s94, v[82:83]
	v_lshl_add_u64 v[56:57], v[56:57], 0, v[94:95]
	global_store_dwordx4 v[56:57], v[106:109], off
	v_mov_b32_dpp v58, v52 row_ror:2 row_mask:0xf bank_mask:0xf
	v_mov_b32_dpp v59, v48 row_ror:2 row_mask:0xf bank_mask:0xf
	v_mov_b32_dpp v56, v52 row_ror:1 row_mask:0xf bank_mask:0xf
	v_mov_b32_dpp v58, v44 row_shr:2 row_mask:0xf bank_mask:0xf
	v_mov_b32_dpp v62, v54 row_ror:1 row_mask:0xf bank_mask:0xf
	v_mov_b32_dpp v92, v54 row_ror:2 row_mask:0xf bank_mask:0xf
	v_mov_b32_dpp v57, v48 row_ror:1 row_mask:0xf bank_mask:0xf
	v_mov_b32_dpp v59, v40 row_shr:2 row_mask:0xf bank_mask:0xf
	v_mov_b32_dpp v56, v44 row_shr:1 row_mask:0xf bank_mask:0xf
	v_mov_b32_dpp v54, v55 row_ror:1 row_mask:0xf bank_mask:0xf
	v_mov_b32_dpp v100, v55 row_ror:2 row_mask:0xf bank_mask:0xf
	v_mov_b32_dpp v57, v40 row_shr:1 row_mask:0xf bank_mask:0xf
	v_pk_fma_f32 v[58:59], v[78:79], v[58:59], v[122:123]
	v_mov_b32_dpp v101, v51 row_ror:2 row_mask:0xf bank_mask:0xf
	v_mov_b32_dpp v100, v47 row_shr:2 row_mask:0xf bank_mask:0xf
	v_pk_fma_f32 v[56:57], v[124:125], v[56:57], v[58:59]
	v_mov_b32_e32 v58, v44
	v_mov_b32_e32 v59, v40
	v_mov_b32_dpp v55, v51 row_ror:1 row_mask:0xf bank_mask:0xf
	v_mov_b32_dpp v101, v43 row_shr:2 row_mask:0xf bank_mask:0xf
	v_mov_b32_dpp v52, v53 row_ror:1 row_mask:0xf bank_mask:0xf
	v_mov_b32_dpp v60, v53 row_ror:2 row_mask:0xf bank_mask:0xf
	v_mov_b32_dpp v54, v47 row_shr:1 row_mask:0xf bank_mask:0xf
	v_pk_fma_f32 v[56:57], v[58:59], v[126:127], v[56:57]
	v_mov_b32_dpp v61, v49 row_ror:2 row_mask:0xf bank_mask:0xf
	v_mov_b32_dpp v63, v50 row_ror:1 row_mask:0xf bank_mask:0xf
	v_mov_b32_dpp v93, v50 row_ror:2 row_mask:0xf bank_mask:0xf
	v_mov_b32_dpp v55, v43 row_shr:1 row_mask:0xf bank_mask:0xf
	v_pk_fma_f32 v[50:51], v[76:77], v[100:101], v[72:73]
	v_mov_b32_dpp v60, v45 row_shr:2 row_mask:0xf bank_mask:0xf
	v_mov_b32_dpp v53, v49 row_ror:1 row_mask:0xf bank_mask:0xf
	v_mov_b32_dpp v61, v41 row_shr:2 row_mask:0xf bank_mask:0xf
	v_pk_fma_f32 v[50:51], v[86:87], v[54:55], v[50:51]
	v_mul_f32_e32 v55, 0x3d372713, v56
	v_mov_b32_dpp v52, v45 row_shr:1 row_mask:0xf bank_mask:0xf
	v_mov_b32_dpp v53, v41 row_shr:1 row_mask:0xf bank_mask:0xf
	v_pk_fma_f32 v[48:49], v[74:75], v[60:61], v[70:71]
	v_mul_f32_e32 v55, v56, v55
	v_mov_b32_dpp v92, v46 row_shr:2 row_mask:0xf bank_mask:0xf
	v_pk_fma_f32 v[48:49], v[84:85], v[52:53], v[48:49]
	v_mov_b32_e32 v52, v45
	v_mov_b32_e32 v53, v41
	v_mov_b32_dpp v93, v42 row_shr:2 row_mask:0xf bank_mask:0xf
	v_fma_f32 v55, v56, v55, v56
	v_mov_b32_dpp v62, v46 row_shr:1 row_mask:0xf bank_mask:0xf
	v_pk_fma_f32 v[48:49], v[52:53], v[66:67], v[48:49]
	v_mov_b32_dpp v63, v42 row_shr:1 row_mask:0xf bank_mask:0xf
	v_pk_fma_f32 v[52:53], v[114:115], v[92:93], v[118:119]
	v_mul_f32_e32 v55, 0x3fcc422a, v55
	v_pk_fma_f32 v[52:53], v[128:129], v[62:63], v[52:53]
	v_mov_b32_e32 v58, v46
	v_mov_b32_e32 v59, v42
	v_mul_f32_e32 v55, 0xbfb8aa3b, v55
	v_pk_fma_f32 v[52:53], v[58:59], v[130:131], v[52:53]
	v_exp_f32_e32 v58, v55
	v_mul_f32_e32 v55, 0x3d372713, v48
	v_mul_f32_e32 v55, v48, v55
	v_fma_f32 v55, v48, v55, v48
	v_add_f32_e32 v58, 1.0, v58
	v_mul_f32_e32 v55, 0x3fcc422a, v55
	v_rcp_f32_e32 v58, v58
	v_mul_f32_e32 v55, 0xbfb8aa3b, v55
; #define LAS __attribute__((address_space(3)))
; __device__ __forceinline__ unsigned cvt_pk_bf16(float lo, float hi) { unsigned r; asm volatile("v_cvt_pk_bf16_f32 %0, %1, %2" : "=v"(r) : "v"(lo), "v"(hi)); return r; }
; __device__ __forceinline__ float gelu_t(float x) { const float u = 1.5957691216f * (x + 0.044715f * x * x * x); return x * sigm(u); }
; __device__ __forceinline__ float dpp_shr1(float old, float src) { return __int_as_float(__builtin_amdgcn_update_dpp(__float_as_int(old), __float_as_int(src), 0x111, 0xf, 0xf, false)); }
; __device__ __forceinline__ float dpp_shr2(float old, float src) { return __int_as_float(__builtin_amdgcn_update_dpp(__float_as_int(old), __float_as_int(src), 0x112, 0xf, 0xf, false)); }
;     __device__ __forceinline__ void operator()(AccT& acc, const Unit& u, int wr, int wc, int fr, int fq) const {
;     ...
;             for (int ai = 0; ai < 2; ++ai) {
;                 f32x4 hv[2]; hv[0] = (f32x4){0.f, 0.f, 0.f, 0.f}; hv[1] = hv[0];
;                 const bool has_pred = (wr == 1) || (ai == 1);
;                 const int pa = (wr == 1) ? ai : 0, pw = (wr == 1) ? 0 : 1;
;                 if (has_pred && fr >= 14) { hv[0] = *(const LAS f32x4*)(xl + xidx(pa, pw, wc, fr - 14, fq, 0, n)); hv[1] = *(const LAS f32x4*)(xl + xidx(pa, pw, wc, fr - 14, fq, 1, n)); }
;     ...
;                 for (int m = 0; m < 4; ++m) {
;                     f32x4 c2[2];
; #pragma unroll
;                     for (int bj = 0; bj < 2; ++bj) { const f32x4 cur = acc[ai][bj][m][n]; const f32x4 pv = (m == 0) ? hv[bj] : acc[ai][bj][m == 0 ? 0 : m - 1][n];
; #pragma unroll
;                         for (int j = 0; j < 4; ++j) { const float p1 = dpp_shr1(dpp_ror1(pv[j]), cur[j]), p2 = dpp_shr2(dpp_ror2(pv[j]), cur[j]);
;                             c2[bj][j] = bia[bj][j] + wgt[bj][0][j] * p2 + wgt[bj][1][j] * p1 + wgt[bj][2][j] * cur[j]; } }
;                     u32x2 w; w.x = cvt_pk_bf16(gelu_t(c2[0][0]) * c2[1][0], gelu_t(c2[0][1]) * c2[1][1]); w.y = cvt_pk_bf16(gelu_t(c2[0][2]) * c2[1][2], gelu_t(c2[0][3]) * c2[1][3]);
;                     if (n == 0) pend[ai][m] = w;
;                     else { u32x4 w4; w4.x = pend[ai][m].x; w4.y = pend[ai][m].y; w4.z = w.x; w4.w = w.y;
;                         *(u32x4*)(F + (size_t)(t0 + ai * 128 + wr * 64 + m * 16 + fr) * FF + cg - 4) = w4; }
	v_mov_b32_e32 v54, v47
	v_exp_f32_e32 v59, v55
	v_mov_b32_e32 v55, v43
	v_pk_fma_f32 v[50:51], v[54:55], v[68:69], v[50:51]
	v_mul_f32_e32 v55, 0x3d372713, v52
	v_mul_f32_e32 v54, v56, v58
	v_mul_f32_e32 v55, v52, v55
	v_mul_f32_e32 v56, 0x3d372713, v50
	v_fma_f32 v55, v52, v55, v52
	v_mul_f32_e32 v56, v50, v56
	v_add_f32_e32 v59, 1.0, v59
	v_mul_f32_e32 v55, 0x3fcc422a, v55
	v_fma_f32 v56, v50, v56, v50
	v_rcp_f32_e32 v59, v59
	v_mul_f32_e32 v55, 0xbfb8aa3b, v55
	v_mul_f32_e32 v56, 0x3fcc422a, v56
	v_exp_f32_e32 v55, v55
	v_mul_f32_e32 v56, 0xbfb8aa3b, v56
	v_exp_f32_e32 v56, v56
	v_mul_f32_e32 v48, v48, v59
	v_mul_f32_e32 v48, v48, v49
	v_add_f32_e32 v49, 1.0, v55
	v_rcp_f32_e32 v49, v49
	v_add_f32_e32 v55, 1.0, v56
	v_rcp_f32_e32 v55, v55
	v_mul_f32_e32 v54, v54, v57
	v_cvt_pk_bf16_f32 v106, v54, v48
	v_mul_f32_e32 v48, v52, v49
	v_mul_f32_e32 v48, v48, v53
	v_mul_f32_e32 v49, v50, v55
	v_mul_f32_e32 v49, v49, v51
	v_cvt_pk_bf16_f32 v107, v48, v49
	v_or_b32_e32 v48, 32, v132
	v_mad_i64_i32 v[48:49], s[8:9], v48, s94, v[82:83]
	v_lshl_add_u64 v[48:49], v[48:49], 0, v[94:95]
	global_store_dwordx4 v[48:49], v[104:107], off
	v_mov_b32_dpp v48, v44 row_ror:1 row_mask:0xf bank_mask:0xf
	v_mov_b32_dpp v50, v44 row_ror:2 row_mask:0xf bank_mask:0xf
	v_mov_b32_dpp v51, v40 row_ror:2 row_mask:0xf bank_mask:0xf
	v_mov_b32_dpp v50, v36 row_shr:2 row_mask:0xf bank_mask:0xf
	v_mov_b32_dpp v44, v45 row_ror:1 row_mask:0xf bank_mask:0xf
	v_mov_b32_dpp v52, v45 row_ror:2 row_mask:0xf bank_mask:0xf
	v_mov_b32_dpp v49, v40 row_ror:1 row_mask:0xf bank_mask:0xf
	v_mov_b32_dpp v51, v32 row_shr:2 row_mask:0xf bank_mask:0xf
	v_mov_b32_dpp v53, v41 row_ror:2 row_mask:0xf bank_mask:0xf
	v_mov_b32_dpp v48, v36 row_shr:1 row_mask:0xf bank_mask:0xf
	v_mov_b32_dpp v52, v37 row_shr:2 row_mask:0xf bank_mask:0xf
	v_mov_b32_dpp v49, v32 row_shr:1 row_mask:0xf bank_mask:0xf
	v_pk_fma_f32 v[50:51], v[78:79], v[50:51], v[122:123]
	v_mov_b32_dpp v45, v41 row_ror:1 row_mask:0xf bank_mask:0xf
	v_mov_b32_dpp v53, v33 row_shr:2 row_mask:0xf bank_mask:0xf
	v_mov_b32_dpp v44, v37 row_shr:1 row_mask:0xf bank_mask:0xf
	v_pk_fma_f32 v[48:49], v[124:125], v[48:49], v[50:51]
	v_mov_b32_e32 v50, v36
	v_mov_b32_e32 v51, v32
	v_mov_b32_dpp v45, v33 row_shr:1 row_mask:0xf bank_mask:0xf
	v_pk_fma_f32 v[40:41], v[74:75], v[52:53], v[70:71]
	v_pk_fma_f32 v[48:49], v[50:51], v[126:127], v[48:49]
	v_pk_fma_f32 v[40:41], v[84:85], v[44:45], v[40:41]
	v_mov_b32_e32 v32, v37
	v_mov_b32_dpp v55, v42 row_ror:1 row_mask:0xf bank_mask:0xf
	v_mov_b32_dpp v57, v42 row_ror:2 row_mask:0xf bank_mask:0xf
	v_pk_fma_f32 v[32:33], v[32:33], v[66:67], v[40:41]
	v_mov_b32_dpp v55, v34 row_shr:1 row_mask:0xf bank_mask:0xf
	v_mov_b32_dpp v57, v34 row_shr:2 row_mask:0xf bank_mask:0xf
	v_mov_b32_e32 v41, v34
	v_mul_f32_e32 v34, 0x3d372713, v48
	v_mul_f32_e32 v34, v48, v34
	v_fma_f32 v34, v48, v34, v48
	v_mul_f32_e32 v34, 0x3fcc422a, v34
	v_mov_b32_dpp v54, v46 row_ror:1 row_mask:0xf bank_mask:0xf
	v_mov_b32_dpp v56, v46 row_ror:2 row_mask:0xf bank_mask:0xf
	v_mul_f32_e32 v34, 0xbfb8aa3b, v34
	v_mov_b32_dpp v54, v38 row_shr:1 row_mask:0xf bank_mask:0xf
	v_mov_b32_dpp v56, v38 row_shr:2 row_mask:0xf bank_mask:0xf
	v_mov_b32_e32 v40, v38
	v_exp_f32_e32 v38, v34
	v_mul_f32_e32 v34, 0x3d372713, v32
	v_mul_f32_e32 v34, v32, v34
	v_fma_f32 v34, v32, v34, v32
	v_mul_f32_e32 v34, 0x3fcc422a, v34
	v_mul_f32_e32 v34, 0xbfb8aa3b, v34
	v_exp_f32_e32 v42, v34
	v_mov_b32_dpp v46, v47 row_ror:1 row_mask:0xf bank_mask:0xf
	v_mov_b32_dpp v58, v47 row_ror:2 row_mask:0xf bank_mask:0xf
	v_mov_b32_e32 v34, v39
	v_mov_b32_dpp v46, v39 row_shr:1 row_mask:0xf bank_mask:0xf
	v_mov_b32_dpp v58, v39 row_shr:2 row_mask:0xf bank_mask:0xf
	v_add_f32_e32 v39, 1.0, v42
	v_pk_fma_f32 v[36:37], v[114:115], v[56:57], v[118:119]
	v_mov_b32_dpp v59, v43 row_ror:2 row_mask:0xf bank_mask:0xf
	v_rcp_f32_e32 v39, v39
	v_pk_fma_f32 v[36:37], v[128:129], v[54:55], v[36:37]
	v_mov_b32_dpp v47, v43 row_ror:1 row_mask:0xf bank_mask:0xf
	v_mov_b32_dpp v59, v35 row_shr:2 row_mask:0xf bank_mask:0xf
	v_pk_fma_f32 v[36:37], v[40:41], v[130:131], v[36:37]
	v_mov_b32_dpp v47, v35 row_shr:1 row_mask:0xf bank_mask:0xf
	v_pk_fma_f32 v[40:41], v[76:77], v[58:59], v[72:73]
	v_mul_f32_e32 v32, v32, v39
	v_pk_fma_f32 v[40:41], v[86:87], v[46:47], v[40:41]
	v_mul_f32_e32 v39, 0x3d372713, v36
	v_pk_fma_f32 v[34:35], v[34:35], v[68:69], v[40:41]
	v_mul_f32_e32 v39, v36, v39
	v_mul_f32_e32 v40, 0x3d372713, v34
	v_fma_f32 v39, v36, v39, v36
	v_mul_f32_e32 v40, v34, v40
	v_mul_f32_e32 v39, 0x3fcc422a, v39
	v_fma_f32 v40, v34, v40, v34
	v_mul_f32_e32 v39, 0xbfb8aa3b, v39
	v_mul_f32_e32 v40, 0x3fcc422a, v40
	v_exp_f32_e32 v39, v39
	v_mul_f32_e32 v40, 0xbfb8aa3b, v40
	v_exp_f32_e32 v40, v40
	v_add_f32_e32 v38, 1.0, v38
	v_rcp_f32_e32 v38, v38
	v_mul_f32_e32 v32, v32, v33
	v_add_f32_e32 v33, 1.0, v39
	v_rcp_f32_e32 v33, v33
	v_add_f32_e32 v39, 1.0, v40
	v_rcp_f32_e32 v39, v39
	v_mul_f32_e32 v38, v48, v38
	v_mul_f32_e32 v38, v38, v49
	v_cvt_pk_bf16_f32 v100, v38, v32
	v_mul_f32_e32 v32, v36, v33
	v_mul_f32_e32 v32, v32, v37
	v_mul_f32_e32 v33, v34, v39
	v_mul_f32_e32 v33, v33, v35
	v_cvt_pk_bf16_f32 v101, v32, v33
	v_or_b32_e32 v32, 48, v132
	v_mad_i64_i32 v[32:33], s[8:9], v32, s94, v[82:83]
	v_lshl_add_u64 v[32:33], v[32:33], 0, v[94:95]
	global_store_dwordx4 v[32:33], v[98:101], off
	v_mov_b32_e32 v91, 0
	v_mov_b32_e32 v92, 0
	v_mov_b32_e32 v93, 0
	v_mov_b32_e32 v32, 0
	v_mov_b32_e32 v33, 0
	v_mov_b32_e32 v34, 0
	v_mov_b32_e32 v35, 0
	s_and_saveexec_b64 s[12:13], s[6:7]
	s_cbranch_execz .LBB0_794
	ds_read_b128 v[32:35], v154 offset:16
	ds_read_b128 v[90:93], v154 offset:48
; #define LAS __attribute__((address_space(3)))
; __device__ __forceinline__ unsigned cvt_pk_bf16(float lo, float hi) { unsigned r; asm volatile("v_cvt_pk_bf16_f32 %0, %1, %2" : "=v"(r) : "v"(lo), "v"(hi)); return r; }
; __device__ __forceinline__ float gelu_t(float x) { const float u = 1.5957691216f * (x + 0.044715f * x * x * x); return x * sigm(u); }
; __device__ __forceinline__ float dpp_shr1(float old, float src) { return __int_as_float(__builtin_amdgcn_update_dpp(__float_as_int(old), __float_as_int(src), 0x111, 0xf, 0xf, false)); }
; __device__ __forceinline__ float dpp_shr2(float old, float src) { return __int_as_float(__builtin_amdgcn_update_dpp(__float_as_int(old), __float_as_int(src), 0x112, 0xf, 0xf, false)); }
;     __device__ __forceinline__ void operator()(AccT& acc, const Unit& u, int wr, int wc, int fr, int fq) const {
;     ...
;             for (int ai = 0; ai < 2; ++ai) {
;                 f32x4 hv[2]; hv[0] = (f32x4){0.f, 0.f, 0.f, 0.f}; hv[1] = hv[0];
;                 const bool has_pred = (wr == 1) || (ai == 1);
;                 const int pa = (wr == 1) ? ai : 0, pw = (wr == 1) ? 0 : 1;
;                 if (has_pred && fr >= 14) { hv[0] = *(const LAS f32x4*)(xl + xidx(pa, pw, wc, fr - 14, fq, 0, n)); hv[1] = *(const LAS f32x4*)(xl + xidx(pa, pw, wc, fr - 14, fq, 1, n)); }
; #pragma unroll
;                 for (int m = 0; m < 4; ++m) {
;                     f32x4 c2[2];
; #pragma unroll
;                     for (int bj = 0; bj < 2; ++bj) { const f32x4 cur = acc[ai][bj][m][n]; const f32x4 pv = (m == 0) ? hv[bj] : acc[ai][bj][m == 0 ? 0 : m - 1][n];
; #pragma unroll
;                         for (int j = 0; j < 4; ++j) { const float p1 = dpp_shr1(dpp_ror1(pv[j]), cur[j]), p2 = dpp_shr2(dpp_ror2(pv[j]), cur[j]);
;                             c2[bj][j] = bia[bj][j] + wgt[bj][0][j] * p2 + wgt[bj][1][j] * p1 + wgt[bj][2][j] * cur[j]; } }
;                     u32x2 w; w.x = cvt_pk_bf16(gelu_t(c2[0][0]) * c2[1][0], gelu_t(c2[0][1]) * c2[1][1]); w.y = cvt_pk_bf16(gelu_t(c2[0][2]) * c2[1][2], gelu_t(c2[0][3]) * c2[1][3]);
;                     if (n == 0) pend[ai][m] = w;
;                     else { u32x4 w4; w4.x = pend[ai][m].x; w4.y = pend[ai][m].y; w4.z = w.x; w4.w = w.y;
;                         *(u32x4*)(F + (size_t)(t0 + ai * 128 + wr * 64 + m * 16 + fr) * FF + cg - 4) = w4; }
.LBB0_794:
	s_or_b64 exec, exec, s[12:13]
	s_waitcnt lgkmcnt(1)
	v_mov_b32_dpp v38, v32 row_ror:2 row_mask:0xf bank_mask:0xf
	s_waitcnt lgkmcnt(0)
	v_mov_b32_dpp v39, v90 row_ror:2 row_mask:0xf bank_mask:0xf
	v_mov_b32_dpp v36, v32 row_ror:1 row_mask:0xf bank_mask:0xf
	v_mov_b32_dpp v38, v28 row_shr:2 row_mask:0xf bank_mask:0xf
	v_mov_b32_dpp v37, v90 row_ror:1 row_mask:0xf bank_mask:0xf
	v_mov_b32_dpp v39, v24 row_shr:2 row_mask:0xf bank_mask:0xf
	v_mov_b32_dpp v36, v28 row_shr:1 row_mask:0xf bank_mask:0xf
	v_mov_b32_dpp v32, v33 row_ror:1 row_mask:0xf bank_mask:0xf
	v_mov_b32_dpp v40, v33 row_ror:2 row_mask:0xf bank_mask:0xf
	v_mov_b32_dpp v37, v24 row_shr:1 row_mask:0xf bank_mask:0xf
	v_pk_fma_f32 v[38:39], v[78:79], v[38:39], v[122:123]
	v_mov_b32_dpp v41, v91 row_ror:2 row_mask:0xf bank_mask:0xf
	v_mov_b32_dpp v40, v29 row_shr:2 row_mask:0xf bank_mask:0xf
	v_pk_fma_f32 v[36:37], v[124:125], v[36:37], v[38:39]
	v_mov_b32_e32 v38, v28
	v_mov_b32_e32 v39, v24
	v_mov_b32_dpp v33, v91 row_ror:1 row_mask:0xf bank_mask:0xf
	v_mov_b32_dpp v41, v25 row_shr:2 row_mask:0xf bank_mask:0xf
	v_mov_b32_dpp v32, v29 row_shr:1 row_mask:0xf bank_mask:0xf
	v_mov_b32_dpp v44, v34 row_ror:2 row_mask:0xf bank_mask:0xf
	v_pk_fma_f32 v[36:37], v[38:39], v[126:127], v[36:37]
	v_mov_b32_dpp v33, v25 row_shr:1 row_mask:0xf bank_mask:0xf
	v_pk_fma_f32 v[38:39], v[74:75], v[40:41], v[70:71]
	v_mov_b32_dpp v45, v92 row_ror:2 row_mask:0xf bank_mask:0xf
	v_mov_b32_dpp v42, v34 row_ror:1 row_mask:0xf bank_mask:0xf
	v_mov_b32_dpp v44, v30 row_shr:2 row_mask:0xf bank_mask:0xf
	v_pk_fma_f32 v[32:33], v[84:85], v[32:33], v[38:39]
	v_mov_b32_e32 v38, v29
	v_mov_b32_e32 v39, v25
	v_mov_b32_dpp v43, v92 row_ror:1 row_mask:0xf bank_mask:0xf
	v_mov_b32_dpp v45, v26 row_shr:2 row_mask:0xf bank_mask:0xf
	v_mov_b32_dpp v42, v30 row_shr:1 row_mask:0xf bank_mask:0xf
	v_mov_b32_dpp v34, v35 row_ror:1 row_mask:0xf bank_mask:0xf
	v_mov_b32_dpp v46, v35 row_ror:2 row_mask:0xf bank_mask:0xf
	v_pk_fma_f32 v[32:33], v[38:39], v[66:67], v[32:33]
	v_mov_b32_dpp v43, v26 row_shr:1 row_mask:0xf bank_mask:0xf
	v_pk_fma_f32 v[38:39], v[114:115], v[44:45], v[118:119]
	v_mov_b32_dpp v47, v93 row_ror:2 row_mask:0xf bank_mask:0xf
	v_mov_b32_dpp v46, v31 row_shr:2 row_mask:0xf bank_mask:0xf
	v_pk_fma_f32 v[38:39], v[128:129], v[42:43], v[38:39]
	v_mov_b32_e32 v40, v30
	v_mov_b32_e32 v41, v26
	v_mov_b32_dpp v35, v93 row_ror:1 row_mask:0xf bank_mask:0xf
	v_mov_b32_dpp v47, v27 row_shr:2 row_mask:0xf bank_mask:0xf
	v_mov_b32_dpp v34, v31 row_shr:1 row_mask:0xf bank_mask:0xf
	v_pk_fma_f32 v[38:39], v[40:41], v[130:131], v[38:39]
	v_mov_b32_dpp v35, v27 row_shr:1 row_mask:0xf bank_mask:0xf
	v_pk_fma_f32 v[40:41], v[76:77], v[46:47], v[72:73]
	v_add_u32_e32 v48, 0x80, v132
	v_pk_fma_f32 v[34:35], v[86:87], v[34:35], v[40:41]
	v_mul_f32_e32 v41, 0x3d372713, v36
	v_mul_f32_e32 v41, v36, v41
	v_fma_f32 v41, v36, v41, v36
	v_mul_f32_e32 v41, 0x3fcc422a, v41
	v_mul_f32_e32 v41, 0xbfb8aa3b, v41
	v_exp_f32_e32 v42, v41
	v_mul_f32_e32 v41, 0x3d372713, v32
	v_mul_f32_e32 v41, v32, v41
	v_fma_f32 v41, v32, v41, v32
	v_add_f32_e32 v42, 1.0, v42
	v_rcp_f32_e32 v42, v42
	v_mul_f32_e32 v41, 0x3fcc422a, v41
	v_mul_f32_e32 v41, 0xbfb8aa3b, v41
	v_mov_b32_e32 v40, v31
	v_exp_f32_e32 v43, v41
	v_mov_b32_e32 v41, v27
	v_pk_fma_f32 v[34:35], v[40:41], v[68:69], v[34:35]
	v_mul_f32_e32 v36, v36, v42
	v_mul_f32_e32 v36, v36, v37
	v_mul_f32_e32 v37, 0x3d372713, v38
	v_mul_f32_e32 v40, 0x3d372713, v34
	v_mul_f32_e32 v37, v38, v37
	v_mul_f32_e32 v40, v34, v40
	v_fma_f32 v37, v38, v37, v38
	v_fma_f32 v40, v34, v40, v34
	v_add_f32_e32 v43, 1.0, v43
	v_mul_f32_e32 v37, 0x3fcc422a, v37
	v_mul_f32_e32 v40, 0x3fcc422a, v40
	v_rcp_f32_e32 v43, v43
	v_mul_f32_e32 v37, 0xbfb8aa3b, v37
	v_mul_f32_e32 v40, 0xbfb8aa3b, v40
	v_exp_f32_e32 v37, v37
	v_exp_f32_e32 v40, v40
	v_mul_f32_e32 v32, v32, v43
	v_mul_f32_e32 v32, v32, v33
	v_add_f32_e32 v33, 1.0, v37
	v_add_f32_e32 v37, 1.0, v40
	v_rcp_f32_e32 v33, v33
	v_rcp_f32_e32 v37, v37
	v_cvt_pk_bf16_f32 v98, v36, v32
	v_mul_f32_e32 v32, v38, v33
	v_mul_f32_e32 v33, v34, v37
	v_mul_f32_e32 v32, v32, v39
	v_mul_f32_e32 v33, v33, v35
	v_cvt_pk_bf16_f32 v99, v32, v33
	v_mov_b64_e32 v[32:33], s[36:37]
	v_mad_i64_i32 v[34:35], s[6:7], v48, s94, v[32:33]
	v_lshl_add_u64 v[34:35], v[34:35], 0, v[94:95]
	global_store_dwordx4 v[34:35], v[96:99], off
	v_mov_b32_dpp v36, v28 row_ror:2 row_mask:0xf bank_mask:0xf
	v_mov_b32_dpp v37, v24 row_ror:2 row_mask:0xf bank_mask:0xf
	v_mov_b32_dpp v34, v28 row_ror:1 row_mask:0xf bank_mask:0xf
	v_mov_b32_dpp v36, v20 row_shr:2 row_mask:0xf bank_mask:0xf
	v_mov_b32_dpp v40, v30 row_ror:1 row_mask:0xf bank_mask:0xf
	v_mov_b32_dpp v42, v30 row_ror:2 row_mask:0xf bank_mask:0xf
	v_mov_b32_dpp v35, v24 row_ror:1 row_mask:0xf bank_mask:0xf
	v_mov_b32_dpp v37, v16 row_shr:2 row_mask:0xf bank_mask:0xf
	v_mov_b32_dpp v34, v20 row_shr:1 row_mask:0xf bank_mask:0xf
	v_mov_b32_dpp v30, v31 row_ror:1 row_mask:0xf bank_mask:0xf
	v_mov_b32_dpp v44, v31 row_ror:2 row_mask:0xf bank_mask:0xf
	v_mov_b32_dpp v35, v16 row_shr:1 row_mask:0xf bank_mask:0xf
	v_pk_fma_f32 v[36:37], v[78:79], v[36:37], v[122:123]
	v_mov_b32_dpp v45, v27 row_ror:2 row_mask:0xf bank_mask:0xf
	v_mov_b32_dpp v44, v23 row_shr:2 row_mask:0xf bank_mask:0xf
	v_pk_fma_f32 v[34:35], v[124:125], v[34:35], v[36:37]
	v_mov_b32_e32 v36, v20
	v_mov_b32_e32 v37, v16
	v_mov_b32_dpp v31, v27 row_ror:1 row_mask:0xf bank_mask:0xf
	v_mov_b32_dpp v45, v19 row_shr:2 row_mask:0xf bank_mask:0xf
	v_mov_b32_dpp v28, v29 row_ror:1 row_mask:0xf bank_mask:0xf
	v_mov_b32_dpp v38, v29 row_ror:2 row_mask:0xf bank_mask:0xf
; __device__ __forceinline__ unsigned cvt_pk_bf16(float lo, float hi) { unsigned r; asm volatile("v_cvt_pk_bf16_f32 %0, %1, %2" : "=v"(r) : "v"(lo), "v"(hi)); return r; }
; __device__ __forceinline__ float gelu_t(float x) { const float u = 1.5957691216f * (x + 0.044715f * x * x * x); return x * sigm(u); }
; __device__ __forceinline__ float dpp_shr1(float old, float src) { return __int_as_float(__builtin_amdgcn_update_dpp(__float_as_int(old), __float_as_int(src), 0x111, 0xf, 0xf, false)); }
; __device__ __forceinline__ float dpp_shr2(float old, float src) { return __int_as_float(__builtin_amdgcn_update_dpp(__float_as_int(old), __float_as_int(src), 0x112, 0xf, 0xf, false)); }
; __device__ __forceinline__ float dpp_ror1(float src) { return __int_as_float(__builtin_amdgcn_update_dpp(0, __float_as_int(src), 0x121, 0xf, 0xf, false)); }
; __device__ __forceinline__ float dpp_ror2(float src) { return __int_as_float(__builtin_amdgcn_update_dpp(0, __float_as_int(src), 0x122, 0xf, 0xf, false)); }
;     __device__ __forceinline__ void operator()(AccT& acc, const Unit& u, int wr, int wc, int fr, int fq) const {
;     ...
;                 for (int m = 0; m < 4; ++m) {
;                     f32x4 c2[2];
; #pragma unroll
;                     for (int bj = 0; bj < 2; ++bj) { const f32x4 cur = acc[ai][bj][m][n]; const f32x4 pv = (m == 0) ? hv[bj] : acc[ai][bj][m == 0 ? 0 : m - 1][n];
; #pragma unroll
;                         for (int j = 0; j < 4; ++j) { const float p1 = dpp_shr1(dpp_ror1(pv[j]), cur[j]), p2 = dpp_shr2(dpp_ror2(pv[j]), cur[j]);
;                             c2[bj][j] = bia[bj][j] + wgt[bj][0][j] * p2 + wgt[bj][1][j] * p1 + wgt[bj][2][j] * cur[j]; } }
;                     u32x2 w; w.x = cvt_pk_bf16(gelu_t(c2[0][0]) * c2[1][0], gelu_t(c2[0][1]) * c2[1][1]); w.y = cvt_pk_bf16(gelu_t(c2[0][2]) * c2[1][2], gelu_t(c2[0][3]) * c2[1][3]);
;                     if (n == 0) pend[ai][m] = w;
;                     else { u32x4 w4; w4.x = pend[ai][m].x; w4.y = pend[ai][m].y; w4.z = w.x; w4.w = w.y;
;                         *(u32x4*)(F + (size_t)(t0 + ai * 128 + wr * 64 + m * 16 + fr) * FF + cg - 4) = w4; }
	v_mov_b32_dpp v30, v23 row_shr:1 row_mask:0xf bank_mask:0xf
	v_pk_fma_f32 v[34:35], v[36:37], v[126:127], v[34:35]
	v_mov_b32_dpp v39, v25 row_ror:2 row_mask:0xf bank_mask:0xf
	v_mov_b32_dpp v41, v26 row_ror:1 row_mask:0xf bank_mask:0xf
	v_mov_b32_dpp v43, v26 row_ror:2 row_mask:0xf bank_mask:0xf
	v_mov_b32_dpp v31, v19 row_shr:1 row_mask:0xf bank_mask:0xf
	v_pk_fma_f32 v[26:27], v[76:77], v[44:45], v[72:73]
	v_mov_b32_dpp v38, v21 row_shr:2 row_mask:0xf bank_mask:0xf
	v_mov_b32_dpp v29, v25 row_ror:1 row_mask:0xf bank_mask:0xf
	v_mov_b32_dpp v39, v17 row_shr:2 row_mask:0xf bank_mask:0xf
	v_pk_fma_f32 v[26:27], v[86:87], v[30:31], v[26:27]
	v_mul_f32_e32 v31, 0x3d372713, v34
	v_mov_b32_dpp v28, v21 row_shr:1 row_mask:0xf bank_mask:0xf
	v_mov_b32_dpp v29, v17 row_shr:1 row_mask:0xf bank_mask:0xf
	v_pk_fma_f32 v[24:25], v[74:75], v[38:39], v[70:71]
	v_mul_f32_e32 v31, v34, v31
	v_mov_b32_dpp v42, v22 row_shr:2 row_mask:0xf bank_mask:0xf
	v_pk_fma_f32 v[24:25], v[84:85], v[28:29], v[24:25]
	v_mov_b32_e32 v28, v21
	v_mov_b32_e32 v29, v17
	v_mov_b32_dpp v43, v18 row_shr:2 row_mask:0xf bank_mask:0xf
	v_fma_f32 v31, v34, v31, v34
	v_mov_b32_dpp v40, v22 row_shr:1 row_mask:0xf bank_mask:0xf
	v_pk_fma_f32 v[24:25], v[28:29], v[66:67], v[24:25]
	v_mov_b32_dpp v41, v18 row_shr:1 row_mask:0xf bank_mask:0xf
	v_pk_fma_f32 v[28:29], v[114:115], v[42:43], v[118:119]
	v_mul_f32_e32 v31, 0x3fcc422a, v31
	v_pk_fma_f32 v[28:29], v[128:129], v[40:41], v[28:29]
	v_mov_b32_e32 v36, v22
	v_mov_b32_e32 v37, v18
	v_mul_f32_e32 v31, 0xbfb8aa3b, v31
	v_pk_fma_f32 v[28:29], v[36:37], v[130:131], v[28:29]
	v_exp_f32_e32 v36, v31
	v_mul_f32_e32 v31, 0x3d372713, v24
	v_mul_f32_e32 v31, v24, v31
	v_fma_f32 v31, v24, v31, v24
	v_add_f32_e32 v36, 1.0, v36
	v_mul_f32_e32 v31, 0x3fcc422a, v31
	v_rcp_f32_e32 v36, v36
	v_mul_f32_e32 v31, 0xbfb8aa3b, v31
	v_mov_b32_e32 v30, v23
	v_exp_f32_e32 v37, v31
	v_mov_b32_e32 v31, v19
	v_pk_fma_f32 v[26:27], v[30:31], v[68:69], v[26:27]
	v_mul_f32_e32 v31, 0x3d372713, v28
	v_mul_f32_e32 v30, v34, v36
	v_mul_f32_e32 v31, v28, v31
	v_mul_f32_e32 v34, 0x3d372713, v26
	v_fma_f32 v31, v28, v31, v28
	v_mul_f32_e32 v34, v26, v34
	v_add_f32_e32 v37, 1.0, v37
	v_mul_f32_e32 v31, 0x3fcc422a, v31
	v_fma_f32 v34, v26, v34, v26
	v_rcp_f32_e32 v37, v37
	v_mul_f32_e32 v31, 0xbfb8aa3b, v31
	v_mul_f32_e32 v34, 0x3fcc422a, v34
	v_exp_f32_e32 v31, v31
	v_mul_f32_e32 v34, 0xbfb8aa3b, v34
	v_exp_f32_e32 v34, v34
	v_mul_f32_e32 v24, v24, v37
	v_mul_f32_e32 v24, v24, v25
	v_add_f32_e32 v25, 1.0, v31
	v_rcp_f32_e32 v25, v25
	v_add_f32_e32 v31, 1.0, v34
	v_rcp_f32_e32 v31, v31
	v_mul_f32_e32 v30, v30, v35
	v_cvt_pk_bf16_f32 v90, v30, v24
	v_mul_f32_e32 v24, v28, v25
	v_mul_f32_e32 v24, v24, v29
	v_mul_f32_e32 v25, v26, v31
	v_mul_f32_e32 v25, v25, v27
	v_cvt_pk_bf16_f32 v91, v24, v25
	v_add_u32_e32 v24, 0x90, v132
	v_mad_i64_i32 v[24:25], s[6:7], v24, s94, v[32:33]
	v_lshl_add_u64 v[24:25], v[24:25], 0, v[94:95]
	global_store_dwordx4 v[24:25], v[88:91], off
	v_mov_b32_dpp v26, v20 row_ror:2 row_mask:0xf bank_mask:0xf
	v_mov_b32_dpp v27, v16 row_ror:2 row_mask:0xf bank_mask:0xf
	v_mov_b32_dpp v24, v20 row_ror:1 row_mask:0xf bank_mask:0xf
	v_mov_b32_dpp v26, v12 row_shr:2 row_mask:0xf bank_mask:0xf
	v_mov_b32_dpp v30, v22 row_ror:1 row_mask:0xf bank_mask:0xf
	v_mov_b32_dpp v34, v22 row_ror:2 row_mask:0xf bank_mask:0xf
	v_mov_b32_dpp v25, v16 row_ror:1 row_mask:0xf bank_mask:0xf
	v_mov_b32_dpp v27, v8 row_shr:2 row_mask:0xf bank_mask:0xf
	v_mov_b32_dpp v24, v12 row_shr:1 row_mask:0xf bank_mask:0xf
	v_mov_b32_dpp v22, v23 row_ror:1 row_mask:0xf bank_mask:0xf
	v_mov_b32_dpp v36, v23 row_ror:2 row_mask:0xf bank_mask:0xf
	v_mov_b32_dpp v25, v8 row_shr:1 row_mask:0xf bank_mask:0xf
	v_pk_fma_f32 v[26:27], v[78:79], v[26:27], v[122:123]
	v_mov_b32_dpp v37, v19 row_ror:2 row_mask:0xf bank_mask:0xf
	v_mov_b32_dpp v36, v15 row_shr:2 row_mask:0xf bank_mask:0xf
	v_pk_fma_f32 v[24:25], v[124:125], v[24:25], v[26:27]
	v_mov_b32_e32 v26, v12
	v_mov_b32_e32 v27, v8
	v_mov_b32_dpp v23, v19 row_ror:1 row_mask:0xf bank_mask:0xf
	v_mov_b32_dpp v37, v11 row_shr:2 row_mask:0xf bank_mask:0xf
	v_mov_b32_dpp v20, v21 row_ror:1 row_mask:0xf bank_mask:0xf
	v_mov_b32_dpp v28, v21 row_ror:2 row_mask:0xf bank_mask:0xf
	v_mov_b32_dpp v22, v15 row_shr:1 row_mask:0xf bank_mask:0xf
	v_pk_fma_f32 v[24:25], v[26:27], v[126:127], v[24:25]
	v_mov_b32_dpp v29, v17 row_ror:2 row_mask:0xf bank_mask:0xf
	v_mov_b32_dpp v31, v18 row_ror:1 row_mask:0xf bank_mask:0xf
	v_mov_b32_dpp v35, v18 row_ror:2 row_mask:0xf bank_mask:0xf
	v_mov_b32_dpp v23, v11 row_shr:1 row_mask:0xf bank_mask:0xf
	v_pk_fma_f32 v[18:19], v[76:77], v[36:37], v[72:73]
	v_mov_b32_dpp v28, v13 row_shr:2 row_mask:0xf bank_mask:0xf
	v_mov_b32_dpp v21, v17 row_ror:1 row_mask:0xf bank_mask:0xf
	v_mov_b32_dpp v29, v9 row_shr:2 row_mask:0xf bank_mask:0xf
	v_pk_fma_f32 v[18:19], v[86:87], v[22:23], v[18:19]
	v_mul_f32_e32 v23, 0x3d372713, v24
	v_mov_b32_dpp v20, v13 row_shr:1 row_mask:0xf bank_mask:0xf
	v_mov_b32_dpp v21, v9 row_shr:1 row_mask:0xf bank_mask:0xf
	v_pk_fma_f32 v[16:17], v[74:75], v[28:29], v[70:71]
	v_mul_f32_e32 v23, v24, v23
	v_mov_b32_dpp v34, v14 row_shr:2 row_mask:0xf bank_mask:0xf
	v_pk_fma_f32 v[16:17], v[84:85], v[20:21], v[16:17]
	v_mov_b32_e32 v20, v13
	v_mov_b32_e32 v21, v9
	v_mov_b32_dpp v35, v10 row_shr:2 row_mask:0xf bank_mask:0xf
	v_fma_f32 v23, v24, v23, v24
	v_mov_b32_dpp v30, v14 row_shr:1 row_mask:0xf bank_mask:0xf
	v_pk_fma_f32 v[16:17], v[20:21], v[66:67], v[16:17]
	v_mov_b32_dpp v31, v10 row_shr:1 row_mask:0xf bank_mask:0xf
	v_pk_fma_f32 v[20:21], v[114:115], v[34:35], v[118:119]
	v_mul_f32_e32 v23, 0x3fcc422a, v23
; __device__ __forceinline__ unsigned cvt_pk_bf16(float lo, float hi) { unsigned r; asm volatile("v_cvt_pk_bf16_f32 %0, %1, %2" : "=v"(r) : "v"(lo), "v"(hi)); return r; }
; __device__ __forceinline__ float gelu_t(float x) { const float u = 1.5957691216f * (x + 0.044715f * x * x * x); return x * sigm(u); }
; __device__ __forceinline__ float dpp_shr1(float old, float src) { return __int_as_float(__builtin_amdgcn_update_dpp(__float_as_int(old), __float_as_int(src), 0x111, 0xf, 0xf, false)); }
; __device__ __forceinline__ float dpp_shr2(float old, float src) { return __int_as_float(__builtin_amdgcn_update_dpp(__float_as_int(old), __float_as_int(src), 0x112, 0xf, 0xf, false)); }
; __device__ __forceinline__ float dpp_ror1(float src) { return __int_as_float(__builtin_amdgcn_update_dpp(0, __float_as_int(src), 0x121, 0xf, 0xf, false)); }
; __device__ __forceinline__ float dpp_ror2(float src) { return __int_as_float(__builtin_amdgcn_update_dpp(0, __float_as_int(src), 0x122, 0xf, 0xf, false)); }
;     __device__ __forceinline__ void operator()(AccT& acc, const Unit& u, int wr, int wc, int fr, int fq) const {
;     ...
;                     for (int bj = 0; bj < 2; ++bj) { const f32x4 cur = acc[ai][bj][m][n]; const f32x4 pv = (m == 0) ? hv[bj] : acc[ai][bj][m == 0 ? 0 : m - 1][n];
; #pragma unroll
;                         for (int j = 0; j < 4; ++j) { const float p1 = dpp_shr1(dpp_ror1(pv[j]), cur[j]), p2 = dpp_shr2(dpp_ror2(pv[j]), cur[j]);
;                             c2[bj][j] = bia[bj][j] + wgt[bj][0][j] * p2 + wgt[bj][1][j] * p1 + wgt[bj][2][j] * cur[j]; } }
;                     u32x2 w; w.x = cvt_pk_bf16(gelu_t(c2[0][0]) * c2[1][0], gelu_t(c2[0][1]) * c2[1][1]); w.y = cvt_pk_bf16(gelu_t(c2[0][2]) * c2[1][2], gelu_t(c2[0][3]) * c2[1][3]);
;                     if (n == 0) pend[ai][m] = w;
;                     else { u32x4 w4; w4.x = pend[ai][m].x; w4.y = pend[ai][m].y; w4.z = w.x; w4.w = w.y;
;                         *(u32x4*)(F + (size_t)(t0 + ai * 128 + wr * 64 + m * 16 + fr) * FF + cg - 4) = w4; }
	v_pk_fma_f32 v[20:21], v[128:129], v[30:31], v[20:21]
	v_mov_b32_e32 v26, v14
	v_mov_b32_e32 v27, v10
	v_mul_f32_e32 v23, 0xbfb8aa3b, v23
	v_pk_fma_f32 v[20:21], v[26:27], v[130:131], v[20:21]
	v_exp_f32_e32 v26, v23
	v_mul_f32_e32 v23, 0x3d372713, v16
	v_mul_f32_e32 v23, v16, v23
	v_fma_f32 v23, v16, v23, v16
	v_add_f32_e32 v26, 1.0, v26
	v_mul_f32_e32 v23, 0x3fcc422a, v23
	v_rcp_f32_e32 v26, v26
	v_mul_f32_e32 v23, 0xbfb8aa3b, v23
	v_mov_b32_e32 v22, v15
	v_exp_f32_e32 v27, v23
	v_mov_b32_e32 v23, v11
	v_pk_fma_f32 v[18:19], v[22:23], v[68:69], v[18:19]
	v_mul_f32_e32 v23, 0x3d372713, v20
	v_mul_f32_e32 v22, v24, v26
	v_mul_f32_e32 v23, v20, v23
	v_mul_f32_e32 v24, 0x3d372713, v18
	v_fma_f32 v23, v20, v23, v20
	v_mul_f32_e32 v24, v18, v24
	v_add_f32_e32 v27, 1.0, v27
	v_mul_f32_e32 v23, 0x3fcc422a, v23
	v_fma_f32 v24, v18, v24, v18
	v_rcp_f32_e32 v27, v27
	v_mul_f32_e32 v23, 0xbfb8aa3b, v23
	v_mul_f32_e32 v24, 0x3fcc422a, v24
	v_exp_f32_e32 v23, v23
	v_mul_f32_e32 v24, 0xbfb8aa3b, v24
	v_exp_f32_e32 v24, v24
	v_mul_f32_e32 v16, v16, v27
	v_mul_f32_e32 v16, v16, v17
	v_add_f32_e32 v17, 1.0, v23
	v_rcp_f32_e32 v17, v17
	v_add_f32_e32 v23, 1.0, v24
	v_rcp_f32_e32 v23, v23
	v_mul_f32_e32 v22, v22, v25
	v_cvt_pk_bf16_f32 v82, v22, v16
	v_mul_f32_e32 v16, v20, v17
	v_mul_f32_e32 v16, v16, v21
	v_mul_f32_e32 v17, v18, v23
	v_mul_f32_e32 v17, v17, v19
	v_cvt_pk_bf16_f32 v83, v16, v17
	v_add_u32_e32 v16, 0xa0, v132
	v_mad_i64_i32 v[16:17], s[6:7], v16, s94, v[32:33]
	v_lshl_add_u64 v[16:17], v[16:17], 0, v[94:95]
	global_store_dwordx4 v[16:17], v[80:83], off
	v_mov_b32_dpp v16, v12 row_ror:1 row_mask:0xf bank_mask:0xf
	v_mov_b32_dpp v18, v12 row_ror:2 row_mask:0xf bank_mask:0xf
	v_mov_b32_dpp v19, v8 row_ror:2 row_mask:0xf bank_mask:0xf
	v_mov_b32_dpp v18, v4 row_shr:2 row_mask:0xf bank_mask:0xf
	v_mov_b32_dpp v12, v13 row_ror:1 row_mask:0xf bank_mask:0xf
	v_mov_b32_dpp v20, v13 row_ror:2 row_mask:0xf bank_mask:0xf
	v_mov_b32_dpp v17, v8 row_ror:1 row_mask:0xf bank_mask:0xf
	v_mov_b32_dpp v19, v0 row_shr:2 row_mask:0xf bank_mask:0xf
	v_mov_b32_dpp v21, v9 row_ror:2 row_mask:0xf bank_mask:0xf
	v_mov_b32_dpp v16, v4 row_shr:1 row_mask:0xf bank_mask:0xf
	v_mov_b32_dpp v20, v5 row_shr:2 row_mask:0xf bank_mask:0xf
	v_mov_b32_dpp v17, v0 row_shr:1 row_mask:0xf bank_mask:0xf
	v_pk_fma_f32 v[18:19], v[78:79], v[18:19], v[122:123]
	v_mov_b32_dpp v13, v9 row_ror:1 row_mask:0xf bank_mask:0xf
	v_mov_b32_dpp v21, v1 row_shr:2 row_mask:0xf bank_mask:0xf
	v_mov_b32_dpp v12, v5 row_shr:1 row_mask:0xf bank_mask:0xf
	v_pk_fma_f32 v[16:17], v[124:125], v[16:17], v[18:19]
	v_mov_b32_e32 v18, v4
	v_mov_b32_e32 v19, v0
	v_mov_b32_dpp v13, v1 row_shr:1 row_mask:0xf bank_mask:0xf
	v_pk_fma_f32 v[8:9], v[74:75], v[20:21], v[70:71]
	v_pk_fma_f32 v[16:17], v[18:19], v[126:127], v[16:17]
	v_pk_fma_f32 v[8:9], v[84:85], v[12:13], v[8:9]
	v_mov_b32_e32 v0, v5
	v_mov_b32_dpp v23, v10 row_ror:1 row_mask:0xf bank_mask:0xf
	v_mov_b32_dpp v25, v10 row_ror:2 row_mask:0xf bank_mask:0xf
	v_pk_fma_f32 v[0:1], v[0:1], v[66:67], v[8:9]
	v_mov_b32_dpp v23, v2 row_shr:1 row_mask:0xf bank_mask:0xf
	v_mov_b32_dpp v25, v2 row_shr:2 row_mask:0xf bank_mask:0xf
	v_mov_b32_e32 v9, v2
	v_mul_f32_e32 v2, 0x3d372713, v16
	v_mul_f32_e32 v2, v16, v2
	v_fma_f32 v2, v16, v2, v16
	v_mul_f32_e32 v2, 0x3fcc422a, v2
	v_mov_b32_dpp v22, v14 row_ror:1 row_mask:0xf bank_mask:0xf
	v_mov_b32_dpp v24, v14 row_ror:2 row_mask:0xf bank_mask:0xf
	v_mul_f32_e32 v2, 0xbfb8aa3b, v2
	v_mov_b32_dpp v22, v6 row_shr:1 row_mask:0xf bank_mask:0xf
	v_mov_b32_dpp v24, v6 row_shr:2 row_mask:0xf bank_mask:0xf
	v_mov_b32_e32 v8, v6
	v_exp_f32_e32 v6, v2
	v_mul_f32_e32 v2, 0x3d372713, v0
	v_mul_f32_e32 v2, v0, v2
	v_fma_f32 v2, v0, v2, v0
	v_mul_f32_e32 v2, 0x3fcc422a, v2
	v_mul_f32_e32 v2, 0xbfb8aa3b, v2
	v_exp_f32_e32 v10, v2
	v_mov_b32_dpp v14, v15 row_ror:1 row_mask:0xf bank_mask:0xf
	v_mov_b32_dpp v26, v15 row_ror:2 row_mask:0xf bank_mask:0xf
	v_mov_b32_e32 v2, v7
	v_mov_b32_dpp v14, v7 row_shr:1 row_mask:0xf bank_mask:0xf
	v_mov_b32_dpp v26, v7 row_shr:2 row_mask:0xf bank_mask:0xf
	v_add_f32_e32 v7, 1.0, v10
	v_pk_fma_f32 v[4:5], v[114:115], v[24:25], v[118:119]
	v_mov_b32_dpp v27, v11 row_ror:2 row_mask:0xf bank_mask:0xf
	v_rcp_f32_e32 v7, v7
	v_pk_fma_f32 v[4:5], v[128:129], v[22:23], v[4:5]
	v_mov_b32_dpp v15, v11 row_ror:1 row_mask:0xf bank_mask:0xf
	v_mov_b32_dpp v27, v3 row_shr:2 row_mask:0xf bank_mask:0xf
	v_pk_fma_f32 v[4:5], v[8:9], v[130:131], v[4:5]
	v_mov_b32_dpp v15, v3 row_shr:1 row_mask:0xf bank_mask:0xf
	v_pk_fma_f32 v[8:9], v[76:77], v[26:27], v[72:73]
	v_mul_f32_e32 v0, v0, v7
	v_pk_fma_f32 v[8:9], v[86:87], v[14:15], v[8:9]
	v_mul_f32_e32 v7, 0x3d372713, v4
	v_pk_fma_f32 v[2:3], v[2:3], v[68:69], v[8:9]
	v_mul_f32_e32 v7, v4, v7
	v_mul_f32_e32 v8, 0x3d372713, v2
	v_fma_f32 v7, v4, v7, v4
	v_mul_f32_e32 v8, v2, v8
	v_mul_f32_e32 v7, 0x3fcc422a, v7
	v_fma_f32 v8, v2, v8, v2
	v_mul_f32_e32 v7, 0xbfb8aa3b, v7
	v_mul_f32_e32 v8, 0x3fcc422a, v8
	v_exp_f32_e32 v7, v7
	v_mul_f32_e32 v8, 0xbfb8aa3b, v8
	v_exp_f32_e32 v8, v8
	v_add_f32_e32 v6, 1.0, v6
	v_rcp_f32_e32 v6, v6
	v_mul_f32_e32 v0, v0, v1
	v_add_f32_e32 v1, 1.0, v7
	v_rcp_f32_e32 v1, v1
	v_add_f32_e32 v7, 1.0, v8
	v_rcp_f32_e32 v7, v7
	v_mul_f32_e32 v6, v16, v6
	v_mul_f32_e32 v6, v6, v17
	v_cvt_pk_bf16_f32 v66, v6, v0
	v_mul_f32_e32 v0, v4, v1
	v_mul_f32_e32 v0, v0, v5
	v_mul_f32_e32 v1, v2, v7
	v_mul_f32_e32 v1, v1, v3
	v_cvt_pk_bf16_f32 v67, v0, v1
	v_add_u32_e32 v0, 0xb0, v132
	v_mad_i64_i32 v[0:1], s[6:7], v0, s94, v[32:33]
	v_lshl_add_u64 v[0:1], v[0:1], 0, v[94:95]
	s_andn2_b64 vcc, exec, s[0:1]
	s_mov_b64 s[0:1], -1
	global_store_dwordx4 v[0:1], v[64:67], off
	s_cbranch_vccnz .LBB0_774
	s_and_b64 vcc, exec, s[4:5]
	s_cbranch_vccnz .LBB0_773
	s_barrier
	s_branch .LBB0_773
